# GEMM2 residual add folded into K-loop as identity-MFMA accumulate (loads spread over iterations, epilogue load round trips removed)
# speedup vs baseline: 1.4926x; 1.4926x over previous
; #define PG8_STAGE(bufoff, gbase) do { _Pragma("unroll") for (int _i = 0; _i < 2; ++_i) \
;         __builtin_amdgcn_global_load_lds((const unsigned*)((const char*)(gbase) + voffA[_i]), (LAS unsigned*)(lds + (bufoff) + ldsw + _i * 8192), 16, 0, 0); } while (0)
; #define PG8_WAIT_V(n) asm volatile("s_waitcnt vmcnt(" #n ")" ::: "memory")
; #define PG8_BAR __builtin_amdgcn_s_barrier()
; template <class Epi, bool SPLITA>
; __device__ __forceinline__ void gemm_phase(LAS unsigned char* lds, const Gemm g, const StaticOrder& S, const Epi& E) {
;     ...
;     PG8_STAGE(PG8_SB(0, 0), cB); PG8_STAGE(PG8_SB(0, 1), cB + hstep); PG8_STAGE_A(PG8_SA(0, 0), cur.pm, 0, 0); PG8_STAGE_A(PG8_SA(0, 1), cur.pm, 0, 1);
;     if (wr == 1) PG8_BAR;
;     PG8_WAIT_V(2); PG8_BAR;
;     PG8_STAGE(PG8_SB(1, 0), cB + kstep); PG8_STAGE_A(PG8_SA(1, 0), cur.pm, 1, 0); PG8_STAGE(PG8_SB(1, 1), cB + hstep + kstep);
;     PG8_WAIT_V(6); PG8_BAR;
;     for (;;) {
.LBB0_477:
	v_lshl_add_u64 v[8:9], s[76:77], 0, v[194:195]
	v_mov_b32_e32 v203, v195
	v_readlane_b32 s6, v254, 35
	s_add_i32 s53, s12, 0x18000
	v_lshl_add_u64 v[10:11], s[76:77], 0, v[202:203]
	v_mov_b32_e32 v205, v195
	v_readlane_b32 s7, v254, 36
	v_mov_b32_e32 v201, v195
	s_and_b32 s1, s1, 3
	v_lshl_add_u64 v[8:9], v[8:9], 0, s[88:89]
	s_mov_b32 m0, s53
	s_add_i32 s64, s12, 0x1a000
	v_lshl_add_u64 v[12:13], s[6:7], 0, v[204:205]
	v_lshl_add_u64 v[14:15], s[6:7], 0, v[200:201]
	s_lshl_b32 s52, s4, 6
	s_lshl_b32 s6, s4, 13
	s_lshl_b32 s7, s1, 12
	s_waitcnt vmcnt(2)
	s_barrier
	global_load_lds_dwordx4 v[8:9], off
	v_lshl_add_u64 v[8:9], v[10:11], 0, s[88:89]
	s_mov_b32 m0, s64
	s_add_i32 s65, s12, 0x8000
	s_add_i32 s85, s12, 0xa000
	global_load_lds_dwordx4 v[8:9], off
	v_lshl_add_u64 v[8:9], v[12:13], 0, s[88:89]
	s_mov_b32 m0, s65
	s_add_u32 s4, s76, 0x40080
	global_load_lds_dwordx4 v[8:9], off
	v_lshl_add_u64 v[8:9], v[14:15], 0, s[88:89]
	s_mov_b32 m0, s85
	s_addc_u32 s5, s77, 0
	s_add_i32 s86, s12, 0x1c000
	global_load_lds_dwordx4 v[8:9], off
	v_lshl_add_u64 v[8:9], s[4:5], 0, v[194:195]
	s_mov_b32 m0, s86
	s_add_i32 s87, s12, 0x1e000
	global_load_lds_dwordx4 v[8:9], off
	v_lshl_add_u64 v[8:9], s[4:5], 0, v[202:203]
	s_mov_b32 m0, s87
	v_lshlrev_b32_e32 v4, 13, v4
	global_load_lds_dwordx4 v[8:9], off
	v_and_b32_e32 v4, 0xffff0000, v4
	v_lshl_add_u32 v206, v3, 4, v4
	v_lshlrev_b32_e32 v3, 13, v6
	v_and_b32_e32 v3, 0xffff0000, v3
	v_bfe_u32 v231, v2, 4, 2
	s_cmpk_lt_u32 s0, 0x100
	v_readlane_b32 s4, v254, 51
	v_lshl_add_u32 v208, v5, 4, v3
	v_and_b32_e32 v230, 15, v2
	v_lshlrev_b32_e32 v3, 4, v231
	v_lshlrev_b32_e32 v2, 2, v2
	s_cselect_b64 s[68:69], -1, 0
	v_readlane_b32 s5, v254, 52
	s_lshl_b32 s4, s1, 2
	v_lshl_or_b32 v3, v230, 6, v3
	v_and_b32_e32 v2, 32, v2
	s_waitcnt vmcnt(6)
	v_writelane_b32 v254, s4, 51
	v_bitop3_b32 v4, v3, s6, v2 bitop3:0xde
	v_bitop3_b32 v2, v3, s7, v2 bitop3:0xde
	v_writelane_b32 v254, s5, 52
	s_lshl_b32 s90, s1, 6
	v_mov_b32_e32 v207, v195
	v_mov_b32_e32 v209, v195
	s_waitcnt lgkmcnt(0)
	s_ashr_i32 s91, s46, 31
	s_mov_b32 s92, 0
	v_add_u32_e32 v232, 0, v2
	v_add_u32_e32 v233, 0, v4
	v_readlane_b32 s94, v254, 30
	v_readlane_b32 s0, v254, 33
	s_barrier
	v_readlane_b32 s1, v254, 34
	v_and_b32_e32 v252, 15, v0
	v_bfe_u32 v253, v0, 4, 2
	v_lshlrev_b32_e32 v253, 2, v253
	v_sub_u32_e32 v252, v252, v253
	v_mov_b32_e32 v253, 0x3c00
	v_cmp_eq_u32_e32 vcc, 0, v252
	s_nop 1
	v_cndmask_b32_e32 v198, 0, v253, vcc
	v_cmp_eq_u32_e32 vcc, 2, v252
	s_nop 1
	v_cndmask_b32_e32 v199, 0, v253, vcc
	v_mov_b32_e32 v253, 0x3c000000
	v_cmp_eq_u32_e32 vcc, 1, v252
	s_nop 1
	v_cndmask_b32_e32 v198, v198, v253, vcc
	v_cmp_eq_u32_e32 vcc, 3, v252
	s_nop 1
	v_cndmask_b32_e32 v199, v199, v253, vcc
	v_lshrrev_b32_e32 v252, 8, v0
	v_lshlrev_b32_e32 v253, 17, v252
	v_and_b32_e32 v252, 15, v0
	v_lshl_or_b32 v253, v252, 11, v253
	v_bfe_u32 v252, v0, 6, 2
	v_lshl_or_b32 v253, v252, 7, v253
	v_bfe_u32 v252, v0, 4, 2
	v_lshl_or_b32 v253, v252, 4, v253
	s_branch .LBB0_480

; #define PG8_LDA(dst, b, h) do { _Pragma("unroll") for (int m = 0; m < 4; ++m) _Pragma("unroll") for (int k = 0; k < 2; ++k) dst[m][k] = *(const LAS f16x8*)(lds + PG8_SA(b, h) + aoff + m * 2048 + k * 1024); } while (0)
; #define PG8_LDB(dst, b, h) do { _Pragma("unroll") for (int n = 0; n < 2; ++n) _Pragma("unroll") for (int k = 0; k < 2; ++k) dst[n][k] = *(const LAS f16x8*)(lds + PG8_SB(b, h) + boff + n * 2048 + k * 1024); } while (0)
; #define PG8_MMA(ai, bj, At, Bt) do { __builtin_amdgcn_s_setprio(1); _Pragma("unroll") for (int m = 0; m < 4; ++m) _Pragma("unroll") for (int n = 0; n < 2; ++n) _Pragma("unroll") for (int k = 0; k < 2; ++k) \
;         acc[ai][bj][m][n] = __builtin_amdgcn_mfma_f32_16x16x32_f16(Bt[n][k], At[m][k], acc[ai][bj][m][n], 0, 0, 0); __builtin_amdgcn_s_setprio(0); } while (0)
; #define PG8_WAIT_V(n) asm volatile("s_waitcnt vmcnt(" #n ")" ::: "memory")
; #define PG8_WAIT_L(n) asm volatile("s_waitcnt lgkmcnt(" #n ")" ::: "memory")
; #define PG8_BAR __builtin_amdgcn_s_barrier()
; #define PG8_SCHED __builtin_amdgcn_sched_barrier(0)
; template <class Epi, bool SPLITA>
; __device__ __forceinline__ void gemm_phase(LAS unsigned char* lds, const Gemm g, const StaticOrder& S, const Epi& E) {
;     ...
;             const int pm2 = last ? npm : cur.pm, kt2 = last ? 0 : t + 2;
;             const char* b2 = last ? nB : cB + (size_t)(t + 2) * kstep; const char* b3 = b2 + kstep;
;             PG8_LDB(B0, 0, 0); PG8_LDB(B1, 0, 1); PG8_SCHED; PG8_LDA(At, 0, 0); PG8_STAGE_A(PG8_SA(1, 1), cur.pm, t + 1, 1);
;             PG8_WAIT_V(8); PG8_WAIT_L(0); PG8_BAR; PG8_MMA(0, 0, At, B0); PG8_MMA(0, 1, At, B1); PG8_BAR; PG8_SCHED;
.LBB0_484:
	s_lshl_b32 s100, s0, 19
	s_lshl_b32 s101, s94, 9
	s_add_u32 s100, s100, s101
	s_lshr_b32 s101, s6, 3
	s_lshl_b32 s101, s101, 18
	s_add_u32 s100, s100, s101
	s_bfe_u32 s101, s6, 0x20001
	s_lshl_b32 s101, s101, 15
	s_add_u32 s100, s100, s101
	s_add_u32 s100, s100, s40
	s_addc_u32 s101, s41, 0
	s_nop 0
	global_load_dwordx4 v[236:239], v253, s[100:101]
	global_load_dwordx4 v[240:243], v253, s[100:101] offset:64
	v_add_u32_e32 v130, 0x10000, v232
	v_add_u32_e32 v142, 0x14000, v232
	ds_read_b128 v[146:149], v130
	ds_read_b128 v[150:153], v130 offset:1024
	ds_read_b128 v[154:157], v130 offset:2048
	ds_read_b128 v[158:161], v130 offset:3072
	ds_read_b128 v[130:133], v142
	ds_read_b128 v[134:137], v142 offset:1024
	ds_read_b128 v[138:141], v142 offset:2048
	ds_read_b128 v[142:145], v142 offset:3072
	ds_read_b128 v[186:189], v233
	ds_read_b128 v[190:193], v233 offset:1024
	ds_read_b128 v[178:181], v233 offset:2048
	ds_read_b128 v[182:185], v233 offset:3072
	ds_read_b128 v[170:173], v233 offset:4096
	ds_read_b128 v[174:177], v233 offset:5120
	ds_read_b128 v[162:165], v233 offset:6144
	ds_read_b128 v[166:169], v233 offset:7168
	s_cmp_lt_u32 s6, 8
	v_mov_b64_e32 v[210:211], v[200:201]
	v_mov_b64_e32 v[212:213], v[204:205]
	s_mov_b64 s[80:81], s[72:73]
	s_cbranch_scc1 .LBB0_486
	s_lshr_b32 s7, s35, 1
	s_add_i32 s7, s7, s1
	s_lshl_b32 s7, s7, 4
	s_or_b32 s66, s7, 8
	s_ashr_i32 s67, s66, 31
	s_lshl_b64 s[66:67], s[66:67], 16
	s_add_u32 s7, s99, s66
	s_addc_u32 s66, s10, s67
	s_add_u32 s80, s7, 0x800
	s_addc_u32 s81, s66, 0
	v_mov_b64_e32 v[210:211], v[208:209]
	v_mov_b64_e32 v[212:213], v[206:207]
.LBB0_486:
	s_add_i32 s7, s6, 2
	s_cmp_eq_u32 s35, 7
	s_cselect_b32 s79, s71, s34
	s_cselect_b32 s78, s98, s11
	s_cselect_b32 s66, 0, s7
	s_cselect_b32 s76, s95, s0
	v_lshl_add_u64 v[196:197], s[80:81], 0, v[212:213]
	s_add_i32 m0, s12, 0xc000
	s_nop 0
	global_load_lds_dwordx4 v[196:197], off
	v_lshl_add_u64 v[196:197], s[80:81], 0, v[210:211]
	s_add_i32 m0, s12, 0xe000
	s_nop 0
	global_load_lds_dwordx4 v[196:197], off
	s_waitcnt vmcnt(10)
	s_waitcnt lgkmcnt(0)
	s_barrier
	s_setprio 1
	s_waitcnt lgkmcnt(0)
	v_mfma_f32_16x16x32_f16 v[126:129], v[146:149], v[186:189], v[126:129]
	v_mfma_f32_16x16x32_f16 v[122:125], v[154:157], v[186:189], v[122:125]
	v_mfma_f32_16x16x32_f16 v[110:113], v[146:149], v[178:181], v[110:113]
	v_mfma_f32_16x16x32_f16 v[106:109], v[154:157], v[178:181], v[106:109]
	v_mfma_f32_16x16x32_f16 v[94:97], v[146:149], v[170:173], v[94:97]
	v_mfma_f32_16x16x32_f16 v[90:93], v[154:157], v[170:173], v[90:93]
	v_mfma_f32_16x16x32_f16 v[78:81], v[146:149], v[162:165], v[78:81]
	v_mfma_f32_16x16x32_f16 v[74:77], v[154:157], v[162:165], v[74:77]
	v_mfma_f32_16x16x32_f16 v[126:129], v[150:153], v[190:193], v[126:129]
	v_mfma_f32_16x16x32_f16 v[122:125], v[158:161], v[190:193], v[122:125]
	v_mfma_f32_16x16x32_f16 v[110:113], v[150:153], v[182:185], v[110:113]
	v_mfma_f32_16x16x32_f16 v[106:109], v[158:161], v[182:185], v[106:109]
	v_mfma_f32_16x16x32_f16 v[94:97], v[150:153], v[174:177], v[94:97]
	v_mfma_f32_16x16x32_f16 v[90:93], v[158:161], v[174:177], v[90:93]
	v_mfma_f32_16x16x32_f16 v[78:81], v[150:153], v[166:169], v[78:81]
	v_mfma_f32_16x16x32_f16 v[74:77], v[158:161], v[166:169], v[74:77]
	s_setprio 0
	s_setprio 1
	v_mfma_f32_16x16x32_f16 v[118:121], v[130:133], v[186:189], v[118:121]
	v_mfma_f32_16x16x32_f16 v[114:117], v[138:141], v[186:189], v[114:117]
	v_mfma_f32_16x16x32_f16 v[102:105], v[130:133], v[178:181], v[102:105]
	v_mfma_f32_16x16x32_f16 v[98:101], v[138:141], v[178:181], v[98:101]
	v_mfma_f32_16x16x32_f16 v[86:89], v[130:133], v[170:173], v[86:89]
	v_mfma_f32_16x16x32_f16 v[82:85], v[138:141], v[170:173], v[82:85]
	v_mfma_f32_16x16x32_f16 v[70:73], v[130:133], v[162:165], v[70:73]
	v_mfma_f32_16x16x32_f16 v[66:69], v[138:141], v[162:165], v[66:69]
	v_mfma_f32_16x16x32_f16 v[118:121], v[134:137], v[190:193], v[118:121]
	v_mfma_f32_16x16x32_f16 v[114:117], v[142:145], v[190:193], v[114:117]
	v_mfma_f32_16x16x32_f16 v[102:105], v[134:137], v[182:185], v[102:105]
	v_mfma_f32_16x16x32_f16 v[98:101], v[142:145], v[182:185], v[98:101]
	v_mfma_f32_16x16x32_f16 v[86:89], v[134:137], v[174:177], v[86:89]
	v_mfma_f32_16x16x32_f16 v[82:85], v[142:145], v[174:177], v[82:85]
	v_mfma_f32_16x16x32_f16 v[70:73], v[134:137], v[166:169], v[70:73]
	v_mfma_f32_16x16x32_f16 v[66:69], v[142:145], v[166:169], v[66:69]
	s_setprio 0
	s_barrier
	v_lshl_add_u64 v[210:211], s[78:79], 0, v[194:195]
	s_mov_b32 m0, s13
	s_add_u32 s80, s78, 0x40000
	ds_read_b128 v[186:189], v233 offset:16384
	ds_read_b128 v[190:193], v233 offset:17408
	ds_read_b128 v[178:181], v233 offset:18432
	ds_read_b128 v[182:185], v233 offset:19456
	ds_read_b128 v[170:173], v233 offset:20480
	ds_read_b128 v[174:177], v233 offset:21504
	ds_read_b128 v[162:165], v233 offset:22528
	ds_read_b128 v[166:169], v233 offset:23552
	global_load_lds_dwordx4 v[210:211], off
	v_lshl_add_u64 v[212:213], s[78:79], 0, v[202:203]
	s_mov_b32 m0, s14
	s_addc_u32 s81, s79, 0
	global_load_lds_dwordx4 v[212:213], off
	v_lshl_add_u64 v[196:197], s[80:81], 0, v[194:195]
	s_mov_b32 m0, s15
	s_cmp_lt_u32 s66, 8
	global_load_lds_dwordx4 v[196:197], off
	v_lshl_add_u64 v[196:197], s[80:81], 0, v[202:203]
	s_mov_b32 m0, s31
	s_cselect_b64 s[80:81], -1, 0
	global_load_lds_dwordx4 v[196:197], off
	s_mov_b64 s[96:97], -1
	s_and_b64 vcc, exec, s[80:81]
	s_cbranch_vccz .LBB0_488
	s_ashr_i32 s77, s76, 31
	s_lshl_b64 s[82:83], s[76:77], 18
	s_add_u32 s67, s62, s82
	s_addc_u32 s77, s63, s83
	s_lshl_b32 s82, s66, 7
	s_add_u32 s82, s67, s82
	s_addc_u32 s83, s77, 0
	s_mov_b64 s[96:97], 0

; #define PG8_STAGE(bufoff, gbase) do { _Pragma("unroll") for (int _i = 0; _i < 2; ++_i) \
;         __builtin_amdgcn_global_load_lds((const unsigned*)((const char*)(gbase) + voffA[_i]), (LAS unsigned*)(lds + (bufoff) + ldsw + _i * 8192), 16, 0, 0); } while (0)
; #define PG8_LDA(dst, b, h) do { _Pragma("unroll") for (int m = 0; m < 4; ++m) _Pragma("unroll") for (int k = 0; k < 2; ++k) dst[m][k] = *(const LAS f16x8*)(lds + PG8_SA(b, h) + aoff + m * 2048 + k * 1024); } while (0)
; #define PG8_LDB(dst, b, h) do { _Pragma("unroll") for (int n = 0; n < 2; ++n) _Pragma("unroll") for (int k = 0; k < 2; ++k) dst[n][k] = *(const LAS f16x8*)(lds + PG8_SB(b, h) + boff + n * 2048 + k * 1024); } while (0)
; #define PG8_MMA(ai, bj, At, Bt) do { __builtin_amdgcn_s_setprio(1); _Pragma("unroll") for (int m = 0; m < 4; ++m) _Pragma("unroll") for (int n = 0; n < 2; ++n) _Pragma("unroll") for (int k = 0; k < 2; ++k) \
;         acc[ai][bj][m][n] = __builtin_amdgcn_mfma_f32_16x16x32_f16(Bt[n][k], At[m][k], acc[ai][bj][m][n], 0, 0, 0); __builtin_amdgcn_s_setprio(0); } while (0)
; #define PG8_WAIT_V(n) asm volatile("s_waitcnt vmcnt(" #n ")" ::: "memory")
; #define PG8_WAIT_L(n) asm volatile("s_waitcnt lgkmcnt(" #n ")" ::: "memory")
; #define PG8_BAR __builtin_amdgcn_s_barrier()
; #define PG8_SCHED __builtin_amdgcn_sched_barrier(0)
; template <class Epi, bool SPLITA>
; __device__ __forceinline__ void gemm_phase(LAS unsigned char* lds, const Gemm g, const StaticOrder& S, const Epi& E) {
;     ...
;             PG8_LDA(At, 0, 1); PG8_STAGE(PG8_SB(0, 0), b2); PG8_STAGE(PG8_SB(0, 1), b2 + hstep); PG8_STAGE_A(PG8_SA(0, 0), pm2, kt2, 0);
;             PG8_WAIT_V(8); PG8_WAIT_L(0); PG8_BAR; PG8_MMA(1, 0, At, B0); PG8_MMA(1, 1, At, B1); PG8_BAR; PG8_SCHED;
;             PG8_LDB(B0, 1, 0); PG8_LDB(B1, 1, 1); PG8_SCHED; PG8_LDA(At, 1, 0); PG8_STAGE_A(PG8_SA(0, 1), pm2, kt2, 1);
;             PG8_WAIT_V(8); PG8_WAIT_L(0); PG8_BAR; PG8_MMA(0, 0, At, B0); PG8_MMA(0, 1, At, B1); PG8_BAR; PG8_SCHED;
.LBB0_490:
	s_mov_b32 m0, s12
	v_lshl_add_u64 v[196:197], s[82:83], 0, v[216:217]
	global_load_lds_dwordx4 v[196:197], off
	v_lshl_add_u64 v[196:197], s[82:83], 0, v[214:215]
	s_mov_b32 m0, s33
	s_nop 0
	global_load_lds_dwordx4 v[196:197], off
	s_waitcnt vmcnt(10)
	s_waitcnt lgkmcnt(0)
	s_barrier
	s_setprio 1
	s_waitcnt lgkmcnt(0)
	v_mfma_f32_16x16x32_f16 v[62:65], v[146:149], v[186:189], v[62:65]
	v_mfma_f32_16x16x32_f16 v[58:61], v[154:157], v[186:189], v[58:61]
	v_mfma_f32_16x16x32_f16 v[46:49], v[146:149], v[178:181], v[46:49]
	v_mfma_f32_16x16x32_f16 v[42:45], v[154:157], v[178:181], v[42:45]
	v_mfma_f32_16x16x32_f16 v[30:33], v[146:149], v[170:173], v[30:33]
	v_mfma_f32_16x16x32_f16 v[26:29], v[154:157], v[170:173], v[26:29]
	v_mfma_f32_16x16x32_f16 v[14:17], v[146:149], v[162:165], v[14:17]
	v_mfma_f32_16x16x32_f16 v[10:13], v[154:157], v[162:165], v[10:13]
	v_mfma_f32_16x16x32_f16 v[62:65], v[150:153], v[190:193], v[62:65]
	v_mfma_f32_16x16x32_f16 v[58:61], v[158:161], v[190:193], v[58:61]
	v_mfma_f32_16x16x32_f16 v[46:49], v[150:153], v[182:185], v[46:49]
	v_mfma_f32_16x16x32_f16 v[42:45], v[158:161], v[182:185], v[42:45]
	v_mfma_f32_16x16x32_f16 v[30:33], v[150:153], v[174:177], v[30:33]
	v_mfma_f32_16x16x32_f16 v[26:29], v[158:161], v[174:177], v[26:29]
	v_mfma_f32_16x16x32_f16 v[14:17], v[150:153], v[166:169], v[14:17]
	v_mfma_f32_16x16x32_f16 v[10:13], v[158:161], v[166:169], v[10:13]
	s_setprio 0
	s_setprio 1
	v_mfma_f32_16x16x32_f16 v[54:57], v[130:133], v[186:189], v[54:57]
	v_mfma_f32_16x16x32_f16 v[50:53], v[138:141], v[186:189], v[50:53]
	v_mfma_f32_16x16x32_f16 v[38:41], v[130:133], v[178:181], v[38:41]
	v_mfma_f32_16x16x32_f16 v[34:37], v[138:141], v[178:181], v[34:37]
	v_mfma_f32_16x16x32_f16 v[22:25], v[130:133], v[170:173], v[22:25]
	v_mfma_f32_16x16x32_f16 v[18:21], v[138:141], v[170:173], v[18:21]
	v_mfma_f32_16x16x32_f16 v[6:9], v[130:133], v[162:165], v[6:9]
	v_mfma_f32_16x16x32_f16 v[2:5], v[138:141], v[162:165], v[2:5]
	v_mfma_f32_16x16x32_f16 v[54:57], v[134:137], v[190:193], v[54:57]
	v_mfma_f32_16x16x32_f16 v[50:53], v[142:145], v[190:193], v[50:53]
	v_mfma_f32_16x16x32_f16 v[38:41], v[134:137], v[182:185], v[38:41]
	v_mfma_f32_16x16x32_f16 v[34:37], v[142:145], v[182:185], v[34:37]
	v_mfma_f32_16x16x32_f16 v[22:25], v[134:137], v[174:177], v[22:25]
	v_mfma_f32_16x16x32_f16 v[18:21], v[142:145], v[174:177], v[18:21]
	v_mfma_f32_16x16x32_f16 v[6:9], v[134:137], v[166:169], v[6:9]
	v_mfma_f32_16x16x32_f16 v[2:5], v[142:145], v[166:169], v[2:5]
	s_setprio 0
	s_barrier
	v_add_u32_e32 v130, 0x18000, v232
	v_add_u32_e32 v142, 0x1c000, v232
	ds_read_b128 v[146:149], v130
	ds_read_b128 v[150:153], v130 offset:1024
	ds_read_b128 v[154:157], v130 offset:2048
	ds_read_b128 v[158:161], v130 offset:3072
	ds_read_b128 v[130:133], v142
	ds_read_b128 v[134:137], v142 offset:1024
	ds_read_b128 v[138:141], v142 offset:2048
	ds_read_b128 v[142:145], v142 offset:3072
	ds_read_b128 v[186:189], v233 offset:32768
	ds_read_b128 v[190:193], v233 offset:33792
	ds_read_b128 v[178:181], v233 offset:34816
	ds_read_b128 v[182:185], v233 offset:35840
	ds_read_b128 v[170:173], v233 offset:36864
	ds_read_b128 v[174:177], v233 offset:37888
	ds_read_b128 v[162:165], v233 offset:38912
	ds_read_b128 v[166:169], v233 offset:39936
	s_mov_b64 s[96:97], -1
	s_and_b64 vcc, exec, s[80:81]
	s_cbranch_vccz .LBB0_492
	s_ashr_i32 s77, s76, 31
	s_lshl_b64 s[82:83], s[76:77], 18
	s_add_u32 s67, s62, s82
	s_addc_u32 s77, s63, s83
	s_lshl_b32 s82, s66, 7
	s_add_u32 s67, s67, s82
	s_addc_u32 s77, s77, 0
	s_add_u32 s82, s67, 0x20000
	s_addc_u32 s83, s77, 0
	s_mov_b64 s[96:97], 0

; #define PG8_STAGE(bufoff, gbase) do { _Pragma("unroll") for (int _i = 0; _i < 2; ++_i) \
;         __builtin_amdgcn_global_load_lds((const unsigned*)((const char*)(gbase) + voffA[_i]), (LAS unsigned*)(lds + (bufoff) + ldsw + _i * 8192), 16, 0, 0); } while (0)
; #define PG8_LDA(dst, b, h) do { _Pragma("unroll") for (int m = 0; m < 4; ++m) _Pragma("unroll") for (int k = 0; k < 2; ++k) dst[m][k] = *(const LAS f16x8*)(lds + PG8_SA(b, h) + aoff + m * 2048 + k * 1024); } while (0)
; #define PG8_LDB(dst, b, h) do { _Pragma("unroll") for (int n = 0; n < 2; ++n) _Pragma("unroll") for (int k = 0; k < 2; ++k) dst[n][k] = *(const LAS f16x8*)(lds + PG8_SB(b, h) + boff + n * 2048 + k * 1024); } while (0)
; #define PG8_MMA(ai, bj, At, Bt) do { __builtin_amdgcn_s_setprio(1); _Pragma("unroll") for (int m = 0; m < 4; ++m) _Pragma("unroll") for (int n = 0; n < 2; ++n) _Pragma("unroll") for (int k = 0; k < 2; ++k) \
;         acc[ai][bj][m][n] = __builtin_amdgcn_mfma_f32_16x16x32_f16(Bt[n][k], At[m][k], acc[ai][bj][m][n], 0, 0, 0); __builtin_amdgcn_s_setprio(0); } while (0)
; #define PG8_WAIT_V(n) asm volatile("s_waitcnt vmcnt(" #n ")" ::: "memory")
; #define PG8_WAIT_L(n) asm volatile("s_waitcnt lgkmcnt(" #n ")" ::: "memory")
; #define PG8_BAR __builtin_amdgcn_s_barrier()
; #define PG8_SCHED __builtin_amdgcn_sched_barrier(0)
; template <class Epi, bool SPLITA>
; __device__ __forceinline__ void gemm_phase(LAS unsigned char* lds, const Gemm g, const StaticOrder& S, const Epi& E) {
;     ...
;             PG8_LDB(B0, 1, 0); PG8_LDB(B1, 1, 1); PG8_SCHED; PG8_LDA(At, 1, 0); PG8_STAGE_A(PG8_SA(0, 1), pm2, kt2, 1);
;             PG8_WAIT_V(8); PG8_WAIT_L(0); PG8_BAR; PG8_MMA(0, 0, At, B0); PG8_MMA(0, 1, At, B1); PG8_BAR; PG8_SCHED;
;             PG8_LDA(At, 1, 1); PG8_STAGE(PG8_SB(1, 0), b3); PG8_STAGE(PG8_SB(1, 1), b3 + hstep); PG8_STAGE_A(PG8_SA(1, 0), pm2, kt2 + 1, 0);
;             PG8_WAIT_V(8); PG8_WAIT_L(0); PG8_BAR; PG8_MMA(1, 0, At, B0); PG8_MMA(1, 1, At, B1); PG8_BAR; PG8_SCHED;
.LBB0_494:
	s_mov_b32 m0, s36
	v_lshl_add_u64 v[196:197], s[82:83], 0, v[216:217]
	global_load_lds_dwordx4 v[196:197], off
	v_lshl_add_u64 v[196:197], s[82:83], 0, v[214:215]
	s_mov_b32 m0, s37
	s_nop 0
	global_load_lds_dwordx4 v[196:197], off
	s_waitcnt vmcnt(8)
	s_waitcnt lgkmcnt(0)
	s_barrier
	s_setprio 1
	s_waitcnt lgkmcnt(0)
	v_mfma_f32_16x16x32_f16 v[126:129], v[146:149], v[186:189], v[126:129]
	v_mfma_f32_16x16x32_f16 v[122:125], v[154:157], v[186:189], v[122:125]
	v_mfma_f32_16x16x32_f16 v[110:113], v[146:149], v[178:181], v[110:113]
	v_mfma_f32_16x16x32_f16 v[106:109], v[154:157], v[178:181], v[106:109]
	v_mfma_f32_16x16x32_f16 v[94:97], v[146:149], v[170:173], v[94:97]
	v_mfma_f32_16x16x32_f16 v[90:93], v[154:157], v[170:173], v[90:93]
	v_mfma_f32_16x16x32_f16 v[78:81], v[146:149], v[162:165], v[78:81]
	v_mfma_f32_16x16x32_f16 v[74:77], v[154:157], v[162:165], v[74:77]
	v_mfma_f32_16x16x32_f16 v[126:129], v[150:153], v[190:193], v[126:129]
	v_mfma_f32_16x16x32_f16 v[122:125], v[158:161], v[190:193], v[122:125]
	v_mfma_f32_16x16x32_f16 v[110:113], v[150:153], v[182:185], v[110:113]
	v_mfma_f32_16x16x32_f16 v[106:109], v[158:161], v[182:185], v[106:109]
	v_mfma_f32_16x16x32_f16 v[94:97], v[150:153], v[174:177], v[94:97]
	v_mfma_f32_16x16x32_f16 v[90:93], v[158:161], v[174:177], v[90:93]
	v_mfma_f32_16x16x32_f16 v[78:81], v[150:153], v[166:169], v[78:81]
	v_mfma_f32_16x16x32_f16 v[74:77], v[158:161], v[166:169], v[74:77]
	s_setprio 0
	s_setprio 1
	v_mfma_f32_16x16x32_f16 v[118:121], v[130:133], v[186:189], v[118:121]
	v_mfma_f32_16x16x32_f16 v[114:117], v[138:141], v[186:189], v[114:117]
	v_mfma_f32_16x16x32_f16 v[102:105], v[130:133], v[178:181], v[102:105]
	v_mfma_f32_16x16x32_f16 v[98:101], v[138:141], v[178:181], v[98:101]
	v_mfma_f32_16x16x32_f16 v[86:89], v[130:133], v[170:173], v[86:89]
	v_mfma_f32_16x16x32_f16 v[82:85], v[138:141], v[170:173], v[82:85]
	v_mfma_f32_16x16x32_f16 v[70:73], v[130:133], v[162:165], v[70:73]
	v_mfma_f32_16x16x32_f16 v[66:69], v[138:141], v[162:165], v[66:69]
	v_mfma_f32_16x16x32_f16 v[118:121], v[134:137], v[190:193], v[118:121]
	v_mfma_f32_16x16x32_f16 v[114:117], v[142:145], v[190:193], v[114:117]
	v_mfma_f32_16x16x32_f16 v[102:105], v[134:137], v[182:185], v[102:105]
	v_mfma_f32_16x16x32_f16 v[98:101], v[142:145], v[182:185], v[98:101]
	v_mfma_f32_16x16x32_f16 v[86:89], v[134:137], v[174:177], v[86:89]
	v_mfma_f32_16x16x32_f16 v[82:85], v[142:145], v[174:177], v[82:85]
	v_mfma_f32_16x16x32_f16 v[70:73], v[134:137], v[166:169], v[70:73]
	v_mfma_f32_16x16x32_f16 v[66:69], v[142:145], v[166:169], v[66:69]
	s_cmp_lt_u32 s6, 8
	s_cbranch_scc0 .Lres_hi
	s_cmp_lt_u32 s6, 4
	s_cbranch_scc0 .Lres_23
	s_cmp_lt_u32 s6, 2
	s_cbranch_scc0 .Lres_1
	v_mfma_f32_16x16x16_f16 v[126:129], v[198:199], v[236:237], v[126:129]
	v_mfma_f32_16x16x16_f16 v[122:125], v[198:199], v[238:239], v[122:125]
	v_mfma_f32_16x16x16_f16 v[118:121], v[198:199], v[240:241], v[118:121]
	v_mfma_f32_16x16x16_f16 v[114:117], v[198:199], v[242:243], v[114:117]
	s_branch .Lres_done
.Lres_1:
	v_mfma_f32_16x16x16_f16 v[110:113], v[198:199], v[236:237], v[110:113]
	v_mfma_f32_16x16x16_f16 v[106:109], v[198:199], v[238:239], v[106:109]
	v_mfma_f32_16x16x16_f16 v[102:105], v[198:199], v[240:241], v[102:105]
	v_mfma_f32_16x16x16_f16 v[98:101], v[198:199], v[242:243], v[98:101]
	s_branch .Lres_done
.Lres_23:
	s_cmp_lt_u32 s6, 6
	s_cbranch_scc0 .Lres_3
	v_mfma_f32_16x16x16_f16 v[94:97], v[198:199], v[236:237], v[94:97]
	v_mfma_f32_16x16x16_f16 v[90:93], v[198:199], v[238:239], v[90:93]
	v_mfma_f32_16x16x16_f16 v[86:89], v[198:199], v[240:241], v[86:89]
	v_mfma_f32_16x16x16_f16 v[82:85], v[198:199], v[242:243], v[82:85]
	s_branch .Lres_done
.Lres_3:
	v_mfma_f32_16x16x16_f16 v[78:81], v[198:199], v[236:237], v[78:81]
	v_mfma_f32_16x16x16_f16 v[74:77], v[198:199], v[238:239], v[74:77]
	v_mfma_f32_16x16x16_f16 v[70:73], v[198:199], v[240:241], v[70:73]
	v_mfma_f32_16x16x16_f16 v[66:69], v[198:199], v[242:243], v[66:69]
	s_branch .Lres_done
.Lres_hi:
	s_cmp_lt_u32 s6, 12
	s_cbranch_scc0 .Lres_67
	s_cmp_lt_u32 s6, 10
	s_cbranch_scc0 .Lres_5
	v_mfma_f32_16x16x16_f16 v[62:65], v[198:199], v[236:237], v[62:65]
	v_mfma_f32_16x16x16_f16 v[58:61], v[198:199], v[238:239], v[58:61]
	v_mfma_f32_16x16x16_f16 v[54:57], v[198:199], v[240:241], v[54:57]
	v_mfma_f32_16x16x16_f16 v[50:53], v[198:199], v[242:243], v[50:53]
	s_branch .Lres_done
.Lres_5:
	v_mfma_f32_16x16x16_f16 v[46:49], v[198:199], v[236:237], v[46:49]
	v_mfma_f32_16x16x16_f16 v[42:45], v[198:199], v[238:239], v[42:45]
	v_mfma_f32_16x16x16_f16 v[38:41], v[198:199], v[240:241], v[38:41]
	v_mfma_f32_16x16x16_f16 v[34:37], v[198:199], v[242:243], v[34:37]
	s_branch .Lres_done
.Lres_67:
	s_cmp_lt_u32 s6, 14
	s_cbranch_scc0 .Lres_7
	v_mfma_f32_16x16x16_f16 v[30:33], v[198:199], v[236:237], v[30:33]
	v_mfma_f32_16x16x16_f16 v[26:29], v[198:199], v[238:239], v[26:29]
	v_mfma_f32_16x16x16_f16 v[22:25], v[198:199], v[240:241], v[22:25]
	v_mfma_f32_16x16x16_f16 v[18:21], v[198:199], v[242:243], v[18:21]
	s_branch .Lres_done
.Lres_7:
	v_mfma_f32_16x16x16_f16 v[14:17], v[198:199], v[236:237], v[14:17]
	v_mfma_f32_16x16x16_f16 v[10:13], v[198:199], v[238:239], v[10:13]
	v_mfma_f32_16x16x16_f16 v[6:9], v[198:199], v[240:241], v[6:9]
	v_mfma_f32_16x16x16_f16 v[2:5], v[198:199], v[242:243], v[2:5]
.Lres_done:
	s_setprio 0
	s_barrier
	s_mov_b32 m0, s53
	v_lshl_add_u64 v[196:197], v[210:211], 0, s[88:89]
	s_add_u32 s78, s78, 0x40080
	ds_read_b128 v[186:189], v233 offset:49152
	ds_read_b128 v[190:193], v233 offset:50176
	ds_read_b128 v[178:181], v233 offset:51200
	ds_read_b128 v[182:185], v233 offset:52224
	ds_read_b128 v[170:173], v233 offset:53248
	ds_read_b128 v[174:177], v233 offset:54272
	ds_read_b128 v[162:165], v233 offset:55296
	ds_read_b128 v[166:169], v233 offset:56320
	global_load_lds_dwordx4 v[196:197], off
	v_lshl_add_u64 v[196:197], v[212:213], 0, s[88:89]
	s_mov_b32 m0, s64
	s_addc_u32 s79, s79, 0
	global_load_lds_dwordx4 v[196:197], off
	v_lshl_add_u64 v[196:197], s[78:79], 0, v[194:195]
	s_mov_b32 m0, s86
	s_mov_b64 s[82:83], -1
	global_load_lds_dwordx4 v[196:197], off
	v_lshl_add_u64 v[196:197], s[78:79], 0, v[202:203]
	s_mov_b32 m0, s87
	s_and_b64 vcc, exec, s[80:81]
	global_load_lds_dwordx4 v[196:197], off
	s_cbranch_vccz .LBB0_496
	s_ashr_i32 s77, s76, 31
	s_lshl_b64 s[78:79], s[76:77], 18
	s_add_u32 s67, s62, s78
	s_addc_u32 s77, s63, s79
	s_lshl_b32 s78, s66, 7
	s_add_u32 s67, s67, s78
	s_addc_u32 s77, s77, 0
	s_add_u32 s78, s67, 0x80
	s_addc_u32 s79, s77, 0
	s_mov_b64 s[82:83], 0

;     __device__ __forceinline__ void operator()(const f32x4 (&acc)[2][2][4][2], const pg8::Unit& u, int, LAS unsigned char*, int wr, int wc, int fr_, int fq_) const {
;     ...
;             f16x8 xh[2][4][2];
; #pragma unroll
;             for (int ai = 0; ai < 2; ++ai)
; #pragma unroll
;                 for (int m = 0; m < 4; ++m)
; #pragma unroll
;                     for (int bj = 0; bj < 2; ++bj) xh[ai][m][bj] = *(const f16x8*)(XH + (size_t)(row0 + ai * 128 + m * 16) * DM + col0 + bj * 32);
; #pragma unroll
;             for (int ai = 0; ai < 2; ++ai)
; #pragma unroll
;                 for (int m = 0; m < 4; ++m) {
;                     float* dst = out + (size_t)(row0 + ai * 128 + m * 16) * DM + col0;
; #pragma unroll
;                     for (int bj = 0; bj < 2; ++bj) {
;                         f32x4 x0, x1;
; #pragma unroll
;                         for (int e = 0; e < 4; ++e) { x0[e] = (float)xh[ai][m][bj][e] + acc[ai][bj][m][0][e]; x1[e] = (float)xh[ai][m][bj][4 + e] + acc[ai][bj][m][1][e]; }
;                         *(f32x4*)(dst + bj * 32) = x0; *(f32x4*)(dst + bj * 32 + 4) = x1;
;                     }
.LBB0_503:
	v_ashrrev_i32_e32 v187, 31, v186
	v_lshl_add_u64 v[130:131], v[188:189], 1, s[40:41]
	v_lshlrev_b64 v[132:133], 11, v[186:187]
	v_lshl_add_u64 v[132:133], v[130:131], 0, v[132:133]
	v_mov_b32_e32 v236, 0
	v_mov_b32_e32 v237, 0
	v_mov_b32_e32 v238, 0
	v_mov_b32_e32 v239, 0
	v_mov_b32_e32 v240, 0
	v_mov_b32_e32 v241, 0
	v_mov_b32_e32 v242, 0
	v_mov_b32_e32 v243, 0
	v_add_u32_e32 v220, 16, v186
	v_ashrrev_i32_e32 v221, 31, v220
	v_lshlrev_b64 v[132:133], 11, v[220:221]
	v_lshl_add_u64 v[132:133], v[130:131], 0, v[132:133]
	v_mov_b32_e32 v182, 0
	v_mov_b32_e32 v183, 0
	v_mov_b32_e32 v184, 0
	v_mov_b32_e32 v185, 0
	v_mov_b32_e32 v178, 0
	v_mov_b32_e32 v179, 0
	v_mov_b32_e32 v180, 0
	v_mov_b32_e32 v181, 0
	v_add_u32_e32 v218, 32, v186
	v_ashrrev_i32_e32 v219, 31, v218
	v_lshlrev_b64 v[132:133], 11, v[218:219]
	v_lshl_add_u64 v[132:133], v[130:131], 0, v[132:133]
	v_mov_b32_e32 v174, 0
	v_mov_b32_e32 v175, 0
	v_mov_b32_e32 v176, 0
	v_mov_b32_e32 v177, 0
	v_mov_b32_e32 v170, 0
	v_mov_b32_e32 v171, 0
	v_mov_b32_e32 v172, 0
	v_mov_b32_e32 v173, 0
	v_add_u32_e32 v216, 48, v186
	v_ashrrev_i32_e32 v217, 31, v216
	v_lshlrev_b64 v[132:133], 11, v[216:217]
	v_lshl_add_u64 v[132:133], v[130:131], 0, v[132:133]
	v_mov_b32_e32 v166, 0
	v_mov_b32_e32 v167, 0
	v_mov_b32_e32 v168, 0
	v_mov_b32_e32 v169, 0
	v_mov_b32_e32 v162, 0
	v_mov_b32_e32 v163, 0
	v_mov_b32_e32 v164, 0
	v_mov_b32_e32 v165, 0
	v_add_u32_e32 v214, 0x80, v186
	v_ashrrev_i32_e32 v215, 31, v214
	v_lshlrev_b64 v[132:133], 11, v[214:215]
	v_lshl_add_u64 v[132:133], v[130:131], 0, v[132:133]
	v_mov_b32_e32 v158, 0
	v_mov_b32_e32 v159, 0
	v_mov_b32_e32 v160, 0
	v_mov_b32_e32 v161, 0
	v_mov_b32_e32 v154, 0
	v_mov_b32_e32 v155, 0
	v_mov_b32_e32 v156, 0
	v_mov_b32_e32 v157, 0
	v_add_u32_e32 v212, 0x90, v186
	v_ashrrev_i32_e32 v213, 31, v212
	v_lshlrev_b64 v[132:133], 11, v[212:213]
	v_add_u32_e32 v210, 0xa0, v186
	v_lshl_add_u64 v[132:133], v[130:131], 0, v[132:133]
	v_ashrrev_i32_e32 v211, 31, v210
	v_mov_b32_e32 v150, 0
	v_mov_b32_e32 v151, 0
	v_mov_b32_e32 v152, 0
	v_mov_b32_e32 v153, 0
	v_mov_b32_e32 v146, 0
	v_mov_b32_e32 v147, 0
	v_mov_b32_e32 v148, 0
	v_mov_b32_e32 v149, 0
	v_lshlrev_b64 v[132:133], 11, v[210:211]
	v_add_u32_e32 v190, 0xb0, v186
	v_lshl_add_u64 v[132:133], v[130:131], 0, v[132:133]
	v_ashrrev_i32_e32 v191, 31, v190
	v_lshlrev_b64 v[192:193], 12, v[186:187]
	v_mov_b32_e32 v142, 0
	v_mov_b32_e32 v143, 0
	v_mov_b32_e32 v144, 0
	v_mov_b32_e32 v145, 0
	v_mov_b32_e32 v138, 0
	v_mov_b32_e32 v139, 0
	v_mov_b32_e32 v140, 0
	v_mov_b32_e32 v141, 0
	v_lshlrev_b64 v[132:133], 11, v[190:191]
	v_lshl_add_u64 v[196:197], s[38:39], 0, v[192:193]
	v_lshlrev_b64 v[192:193], 2, v[188:189]
	v_lshl_add_u64 v[130:131], v[130:131], 0, v[132:133]
	v_lshl_add_u64 v[196:197], v[196:197], 0, v[192:193]
	v_mov_b32_e32 v134, 0
	v_mov_b32_e32 v135, 0
	v_mov_b32_e32 v136, 0
	v_mov_b32_e32 v137, 0
	s_nop 0
	v_mov_b32_e32 v130, 0
	v_mov_b32_e32 v131, 0
	v_mov_b32_e32 v132, 0
	v_mov_b32_e32 v133, 0
	v_cvt_f32_f16_e32 v226, v236
	v_cvt_f32_f16_sdwa v227, v236 dst_sel:DWORD dst_unused:UNUSED_PAD src0_sel:WORD_1
	v_cvt_f32_f16_e32 v248, v238
	v_cvt_f32_f16_sdwa v249, v238 dst_sel:DWORD dst_unused:UNUSED_PAD src0_sel:WORD_1
	v_cvt_f32_f16_e32 v236, v237
	v_cvt_f32_f16_sdwa v237, v237 dst_sel:DWORD dst_unused:UNUSED_PAD src0_sel:WORD_1
	v_pk_add_f32 v[244:245], v[126:127], v[226:227]
	v_cvt_f32_f16_e32 v226, v239
	v_cvt_f32_f16_sdwa v227, v239 dst_sel:DWORD dst_unused:UNUSED_PAD src0_sel:WORD_1
	v_pk_add_f32 v[246:247], v[128:129], v[236:237]
	v_pk_add_f32 v[236:237], v[122:123], v[248:249]
	v_pk_add_f32 v[238:239], v[124:125], v[226:227]
	global_store_dwordx4 v[196:197], v[244:247], off
	global_store_dwordx4 v[196:197], v[236:239], off offset:16
	v_cvt_f32_f16_e32 v226, v240
	v_cvt_f32_f16_sdwa v227, v240 dst_sel:DWORD dst_unused:UNUSED_PAD src0_sel:WORD_1
	v_cvt_f32_f16_e32 v236, v241
	v_cvt_f32_f16_sdwa v237, v241 dst_sel:DWORD dst_unused:UNUSED_PAD src0_sel:WORD_1
	v_cvt_f32_f16_e32 v244, v242
	v_cvt_f32_f16_sdwa v245, v242 dst_sel:DWORD dst_unused:UNUSED_PAD src0_sel:WORD_1
	v_pk_add_f32 v[238:239], v[120:121], v[236:237]
	v_pk_add_f32 v[236:237], v[118:119], v[226:227]
	v_cvt_f32_f16_e32 v226, v243
	v_cvt_f32_f16_sdwa v227, v243 dst_sel:DWORD dst_unused:UNUSED_PAD src0_sel:WORD_1
	v_pk_add_f32 v[240:241], v[114:115], v[244:245]
	v_pk_add_f32 v[242:243], v[116:117], v[226:227]
	global_store_dwordx4 v[196:197], v[236:239], off offset:128
	global_store_dwordx4 v[196:197], v[240:243], off offset:144
	v_lshlrev_b64 v[196:197], 12, v[220:221]
	v_cvt_f32_f16_e32 v220, v182
	v_cvt_f32_f16_sdwa v221, v182 dst_sel:DWORD dst_unused:UNUSED_PAD src0_sel:WORD_1
	v_cvt_f32_f16_e32 v182, v183
	v_cvt_f32_f16_sdwa v183, v183 dst_sel:DWORD dst_unused:UNUSED_PAD src0_sel:WORD_1
	v_cvt_f32_f16_e32 v226, v184
	v_cvt_f32_f16_sdwa v227, v184 dst_sel:DWORD dst_unused:UNUSED_PAD src0_sel:WORD_1
	v_lshl_add_u64 v[196:197], s[38:39], 0, v[196:197]
	v_pk_add_f32 v[238:239], v[112:113], v[182:183]
	v_cvt_f32_f16_e32 v182, v185
	v_cvt_f32_f16_sdwa v183, v185 dst_sel:DWORD dst_unused:UNUSED_PAD src0_sel:WORD_1
	v_lshl_add_u64 v[196:197], v[196:197], 0, v[192:193]
	v_pk_add_f32 v[236:237], v[110:111], v[220:221]
	v_cvt_f32_f16_e32 v220, v180
	v_pk_add_f32 v[184:185], v[108:109], v[182:183]
	v_pk_add_f32 v[182:183], v[106:107], v[226:227]
	global_store_dwordx4 v[196:197], v[236:239], off
	global_store_dwordx4 v[196:197], v[182:185], off offset:16
	v_cvt_f32_f16_sdwa v221, v180 dst_sel:DWORD dst_unused:UNUSED_PAD src0_sel:WORD_1
	s_nop 0
	v_cvt_f32_f16_e32 v182, v178
	v_cvt_f32_f16_sdwa v183, v178 dst_sel:DWORD dst_unused:UNUSED_PAD src0_sel:WORD_1
;     __device__ __forceinline__ void operator()(const f32x4 (&acc)[2][2][4][2], const pg8::Unit& u, int, LAS unsigned char*, int wr, int wc, int fr_, int fq_) const {
;     ...
;             for (int ai = 0; ai < 2; ++ai)
; #pragma unroll
;                 for (int m = 0; m < 4; ++m) {
;                     float* dst = out + (size_t)(row0 + ai * 128 + m * 16) * DM + col0;
; #pragma unroll
;                     for (int bj = 0; bj < 2; ++bj) {
;                         f32x4 x0, x1;
; #pragma unroll
;                         for (int e = 0; e < 4; ++e) { x0[e] = (float)xh[ai][m][bj][e] + acc[ai][bj][m][0][e]; x1[e] = (float)xh[ai][m][bj][4 + e] + acc[ai][bj][m][1][e]; }
;                         *(f32x4*)(dst + bj * 32) = x0; *(f32x4*)(dst + bj * 32 + 4) = x1;
;                     }
	v_cvt_f32_f16_e32 v178, v179
	v_cvt_f32_f16_sdwa v179, v179 dst_sel:DWORD dst_unused:UNUSED_PAD src0_sel:WORD_1
	v_pk_add_f32 v[182:183], v[102:103], v[182:183]
	v_pk_add_f32 v[184:185], v[104:105], v[178:179]
	v_cvt_f32_f16_e32 v178, v181
	v_cvt_f32_f16_sdwa v179, v181 dst_sel:DWORD dst_unused:UNUSED_PAD src0_sel:WORD_1
	v_pk_add_f32 v[180:181], v[100:101], v[178:179]
	v_pk_add_f32 v[178:179], v[98:99], v[220:221]
	global_store_dwordx4 v[196:197], v[182:185], off offset:128
	global_store_dwordx4 v[196:197], v[178:181], off offset:144
	s_nop 0
	v_cvt_f32_f16_e32 v184, v176
	v_lshlrev_b64 v[178:179], 12, v[218:219]
	v_lshl_add_u64 v[178:179], s[38:39], 0, v[178:179]
	v_lshl_add_u64 v[182:183], v[178:179], 0, v[192:193]
	v_cvt_f32_f16_e32 v178, v174
	v_cvt_f32_f16_sdwa v179, v174 dst_sel:DWORD dst_unused:UNUSED_PAD src0_sel:WORD_1
	v_cvt_f32_f16_e32 v174, v175
	v_cvt_f32_f16_sdwa v175, v175 dst_sel:DWORD dst_unused:UNUSED_PAD src0_sel:WORD_1
	v_cvt_f32_f16_sdwa v185, v176 dst_sel:DWORD dst_unused:UNUSED_PAD src0_sel:WORD_1
	v_pk_add_f32 v[178:179], v[94:95], v[178:179]
	v_pk_add_f32 v[180:181], v[96:97], v[174:175]
	v_cvt_f32_f16_e32 v174, v177
	v_cvt_f32_f16_sdwa v175, v177 dst_sel:DWORD dst_unused:UNUSED_PAD src0_sel:WORD_1
	v_pk_add_f32 v[176:177], v[92:93], v[174:175]
	v_pk_add_f32 v[174:175], v[90:91], v[184:185]
	global_store_dwordx4 v[182:183], v[178:181], off
	global_store_dwordx4 v[182:183], v[174:177], off offset:16
	s_nop 0
	v_cvt_f32_f16_e32 v178, v172
	v_cvt_f32_f16_e32 v174, v170
	v_cvt_f32_f16_sdwa v175, v170 dst_sel:DWORD dst_unused:UNUSED_PAD src0_sel:WORD_1
	v_cvt_f32_f16_e32 v170, v171
	v_cvt_f32_f16_sdwa v171, v171 dst_sel:DWORD dst_unused:UNUSED_PAD src0_sel:WORD_1
	v_cvt_f32_f16_sdwa v179, v172 dst_sel:DWORD dst_unused:UNUSED_PAD src0_sel:WORD_1
	v_pk_add_f32 v[174:175], v[86:87], v[174:175]
	v_pk_add_f32 v[176:177], v[88:89], v[170:171]
	v_cvt_f32_f16_e32 v170, v173
	v_cvt_f32_f16_sdwa v171, v173 dst_sel:DWORD dst_unused:UNUSED_PAD src0_sel:WORD_1
	v_pk_add_f32 v[172:173], v[84:85], v[170:171]
	v_pk_add_f32 v[170:171], v[82:83], v[178:179]
	global_store_dwordx4 v[182:183], v[174:177], off offset:128
	global_store_dwordx4 v[182:183], v[170:173], off offset:144
	s_nop 0
	v_cvt_f32_f16_e32 v176, v168
	v_lshlrev_b64 v[170:171], 12, v[216:217]
	v_lshl_add_u64 v[170:171], s[38:39], 0, v[170:171]
	v_lshl_add_u64 v[174:175], v[170:171], 0, v[192:193]
	v_cvt_f32_f16_e32 v170, v166
	v_cvt_f32_f16_sdwa v171, v166 dst_sel:DWORD dst_unused:UNUSED_PAD src0_sel:WORD_1
	v_cvt_f32_f16_e32 v166, v167
	v_cvt_f32_f16_sdwa v167, v167 dst_sel:DWORD dst_unused:UNUSED_PAD src0_sel:WORD_1
	v_cvt_f32_f16_sdwa v177, v168 dst_sel:DWORD dst_unused:UNUSED_PAD src0_sel:WORD_1
	v_pk_add_f32 v[170:171], v[78:79], v[170:171]
	v_pk_add_f32 v[172:173], v[80:81], v[166:167]
	v_cvt_f32_f16_e32 v166, v169
	v_cvt_f32_f16_sdwa v167, v169 dst_sel:DWORD dst_unused:UNUSED_PAD src0_sel:WORD_1
	v_pk_add_f32 v[168:169], v[76:77], v[166:167]
	v_pk_add_f32 v[166:167], v[74:75], v[176:177]
	global_store_dwordx4 v[174:175], v[170:173], off
	global_store_dwordx4 v[174:175], v[166:169], off offset:16
	s_nop 0
	v_cvt_f32_f16_e32 v170, v164
	v_cvt_f32_f16_e32 v166, v162
	v_cvt_f32_f16_sdwa v167, v162 dst_sel:DWORD dst_unused:UNUSED_PAD src0_sel:WORD_1
	v_cvt_f32_f16_e32 v162, v163
	v_cvt_f32_f16_sdwa v163, v163 dst_sel:DWORD dst_unused:UNUSED_PAD src0_sel:WORD_1
	v_cvt_f32_f16_sdwa v171, v164 dst_sel:DWORD dst_unused:UNUSED_PAD src0_sel:WORD_1
	v_pk_add_f32 v[166:167], v[70:71], v[166:167]
	v_pk_add_f32 v[168:169], v[72:73], v[162:163]
	v_cvt_f32_f16_e32 v162, v165
	v_cvt_f32_f16_sdwa v163, v165 dst_sel:DWORD dst_unused:UNUSED_PAD src0_sel:WORD_1
	v_pk_add_f32 v[164:165], v[68:69], v[162:163]
	v_pk_add_f32 v[162:163], v[66:67], v[170:171]
	global_store_dwordx4 v[174:175], v[166:169], off offset:128
	global_store_dwordx4 v[174:175], v[162:165], off offset:144
	s_nop 0
	v_cvt_f32_f16_e32 v168, v160
	v_lshlrev_b64 v[162:163], 12, v[214:215]
	v_lshl_add_u64 v[162:163], s[38:39], 0, v[162:163]
	v_lshl_add_u64 v[166:167], v[162:163], 0, v[192:193]
	v_cvt_f32_f16_e32 v162, v158
	v_cvt_f32_f16_sdwa v163, v158 dst_sel:DWORD dst_unused:UNUSED_PAD src0_sel:WORD_1
	v_cvt_f32_f16_e32 v158, v159
	v_cvt_f32_f16_sdwa v159, v159 dst_sel:DWORD dst_unused:UNUSED_PAD src0_sel:WORD_1
	v_cvt_f32_f16_sdwa v169, v160 dst_sel:DWORD dst_unused:UNUSED_PAD src0_sel:WORD_1
	v_pk_add_f32 v[162:163], v[62:63], v[162:163]
	v_pk_add_f32 v[164:165], v[64:65], v[158:159]
	v_cvt_f32_f16_e32 v158, v161
	v_cvt_f32_f16_sdwa v159, v161 dst_sel:DWORD dst_unused:UNUSED_PAD src0_sel:WORD_1
	v_pk_add_f32 v[160:161], v[60:61], v[158:159]
	v_pk_add_f32 v[158:159], v[58:59], v[168:169]
	global_store_dwordx4 v[166:167], v[162:165], off
	global_store_dwordx4 v[166:167], v[158:161], off offset:16
	s_nop 0
	v_cvt_f32_f16_e32 v162, v156
	v_cvt_f32_f16_e32 v158, v154
	v_cvt_f32_f16_sdwa v159, v154 dst_sel:DWORD dst_unused:UNUSED_PAD src0_sel:WORD_1
	v_cvt_f32_f16_e32 v154, v155
	v_cvt_f32_f16_sdwa v155, v155 dst_sel:DWORD dst_unused:UNUSED_PAD src0_sel:WORD_1
	v_cvt_f32_f16_sdwa v163, v156 dst_sel:DWORD dst_unused:UNUSED_PAD src0_sel:WORD_1
	v_pk_add_f32 v[158:159], v[54:55], v[158:159]
	v_pk_add_f32 v[160:161], v[56:57], v[154:155]
	v_cvt_f32_f16_e32 v154, v157
	v_cvt_f32_f16_sdwa v155, v157 dst_sel:DWORD dst_unused:UNUSED_PAD src0_sel:WORD_1
	v_pk_add_f32 v[156:157], v[52:53], v[154:155]
	v_pk_add_f32 v[154:155], v[50:51], v[162:163]
	global_store_dwordx4 v[166:167], v[158:161], off offset:128
	global_store_dwordx4 v[166:167], v[154:157], off offset:144
	s_nop 0
	v_cvt_f32_f16_e32 v160, v152
	v_lshlrev_b64 v[154:155], 12, v[212:213]
;     __device__ __forceinline__ void operator()(const f32x4 (&acc)[2][2][4][2], const pg8::Unit& u, int, LAS unsigned char*, int wr, int wc, int fr_, int fq_) const {
;     ...
;             for (int ai = 0; ai < 2; ++ai)
; #pragma unroll
;                 for (int m = 0; m < 4; ++m) {
;                     float* dst = out + (size_t)(row0 + ai * 128 + m * 16) * DM + col0;
; #pragma unroll
;                     for (int bj = 0; bj < 2; ++bj) {
;                         f32x4 x0, x1;
; #pragma unroll
;                         for (int e = 0; e < 4; ++e) { x0[e] = (float)xh[ai][m][bj][e] + acc[ai][bj][m][0][e]; x1[e] = (float)xh[ai][m][bj][4 + e] + acc[ai][bj][m][1][e]; }
;                         *(f32x4*)(dst + bj * 32) = x0; *(f32x4*)(dst + bj * 32 + 4) = x1;
;                     }
	v_lshl_add_u64 v[154:155], s[38:39], 0, v[154:155]
	v_lshl_add_u64 v[158:159], v[154:155], 0, v[192:193]
	v_cvt_f32_f16_e32 v154, v150
	v_cvt_f32_f16_sdwa v155, v150 dst_sel:DWORD dst_unused:UNUSED_PAD src0_sel:WORD_1
	v_cvt_f32_f16_e32 v150, v151
	v_cvt_f32_f16_sdwa v151, v151 dst_sel:DWORD dst_unused:UNUSED_PAD src0_sel:WORD_1
	v_cvt_f32_f16_sdwa v161, v152 dst_sel:DWORD dst_unused:UNUSED_PAD src0_sel:WORD_1
	v_pk_add_f32 v[154:155], v[46:47], v[154:155]
	v_pk_add_f32 v[156:157], v[48:49], v[150:151]
	v_cvt_f32_f16_e32 v150, v153
	v_cvt_f32_f16_sdwa v151, v153 dst_sel:DWORD dst_unused:UNUSED_PAD src0_sel:WORD_1
	v_pk_add_f32 v[152:153], v[44:45], v[150:151]
	v_pk_add_f32 v[150:151], v[42:43], v[160:161]
	global_store_dwordx4 v[158:159], v[154:157], off
	global_store_dwordx4 v[158:159], v[150:153], off offset:16
	s_nop 0
	v_cvt_f32_f16_e32 v154, v148
	v_cvt_f32_f16_e32 v150, v146
	v_cvt_f32_f16_sdwa v151, v146 dst_sel:DWORD dst_unused:UNUSED_PAD src0_sel:WORD_1
	v_cvt_f32_f16_e32 v146, v147
	v_cvt_f32_f16_sdwa v147, v147 dst_sel:DWORD dst_unused:UNUSED_PAD src0_sel:WORD_1
	v_cvt_f32_f16_sdwa v155, v148 dst_sel:DWORD dst_unused:UNUSED_PAD src0_sel:WORD_1
	v_pk_add_f32 v[150:151], v[38:39], v[150:151]
	v_pk_add_f32 v[152:153], v[40:41], v[146:147]
	v_cvt_f32_f16_e32 v146, v149
	v_cvt_f32_f16_sdwa v147, v149 dst_sel:DWORD dst_unused:UNUSED_PAD src0_sel:WORD_1
	v_pk_add_f32 v[148:149], v[36:37], v[146:147]
	v_pk_add_f32 v[146:147], v[34:35], v[154:155]
	global_store_dwordx4 v[158:159], v[150:153], off offset:128
	global_store_dwordx4 v[158:159], v[146:149], off offset:144
	s_nop 0
	v_cvt_f32_f16_e32 v152, v144
	v_lshlrev_b64 v[146:147], 12, v[210:211]
	v_lshl_add_u64 v[146:147], s[38:39], 0, v[146:147]
	v_lshl_add_u64 v[150:151], v[146:147], 0, v[192:193]
	v_cvt_f32_f16_e32 v146, v142
	v_cvt_f32_f16_sdwa v147, v142 dst_sel:DWORD dst_unused:UNUSED_PAD src0_sel:WORD_1
	v_cvt_f32_f16_e32 v142, v143
	v_cvt_f32_f16_sdwa v143, v143 dst_sel:DWORD dst_unused:UNUSED_PAD src0_sel:WORD_1
	v_cvt_f32_f16_sdwa v153, v144 dst_sel:DWORD dst_unused:UNUSED_PAD src0_sel:WORD_1
	v_pk_add_f32 v[146:147], v[30:31], v[146:147]
	v_pk_add_f32 v[148:149], v[32:33], v[142:143]
	v_cvt_f32_f16_e32 v142, v145
	v_cvt_f32_f16_sdwa v143, v145 dst_sel:DWORD dst_unused:UNUSED_PAD src0_sel:WORD_1
	v_pk_add_f32 v[144:145], v[28:29], v[142:143]
	v_pk_add_f32 v[142:143], v[26:27], v[152:153]
	global_store_dwordx4 v[150:151], v[146:149], off
	global_store_dwordx4 v[150:151], v[142:145], off offset:16
	s_nop 0
	v_cvt_f32_f16_e32 v146, v140
	v_cvt_f32_f16_e32 v142, v138
	v_cvt_f32_f16_sdwa v143, v138 dst_sel:DWORD dst_unused:UNUSED_PAD src0_sel:WORD_1
	v_cvt_f32_f16_e32 v138, v139
	v_cvt_f32_f16_sdwa v139, v139 dst_sel:DWORD dst_unused:UNUSED_PAD src0_sel:WORD_1
	v_cvt_f32_f16_sdwa v147, v140 dst_sel:DWORD dst_unused:UNUSED_PAD src0_sel:WORD_1
	v_pk_add_f32 v[142:143], v[22:23], v[142:143]
	v_pk_add_f32 v[144:145], v[24:25], v[138:139]
	v_cvt_f32_f16_e32 v138, v141
	v_cvt_f32_f16_sdwa v139, v141 dst_sel:DWORD dst_unused:UNUSED_PAD src0_sel:WORD_1
	v_pk_add_f32 v[140:141], v[20:21], v[138:139]
	v_pk_add_f32 v[138:139], v[18:19], v[146:147]
	global_store_dwordx4 v[150:151], v[142:145], off offset:128
	global_store_dwordx4 v[150:151], v[138:141], off offset:144
	s_nop 0
	v_cvt_f32_f16_e32 v144, v136
	v_lshlrev_b64 v[138:139], 12, v[190:191]
	v_lshl_add_u64 v[138:139], s[38:39], 0, v[138:139]
	v_lshl_add_u64 v[142:143], v[138:139], 0, v[192:193]
	v_cvt_f32_f16_e32 v138, v134
	v_cvt_f32_f16_sdwa v139, v134 dst_sel:DWORD dst_unused:UNUSED_PAD src0_sel:WORD_1
	v_cvt_f32_f16_e32 v134, v135
	v_cvt_f32_f16_sdwa v135, v135 dst_sel:DWORD dst_unused:UNUSED_PAD src0_sel:WORD_1
	v_cvt_f32_f16_sdwa v145, v136 dst_sel:DWORD dst_unused:UNUSED_PAD src0_sel:WORD_1
	v_pk_add_f32 v[138:139], v[14:15], v[138:139]
	v_pk_add_f32 v[140:141], v[16:17], v[134:135]
	v_cvt_f32_f16_e32 v134, v137
	v_cvt_f32_f16_sdwa v135, v137 dst_sel:DWORD dst_unused:UNUSED_PAD src0_sel:WORD_1
	v_pk_add_f32 v[136:137], v[12:13], v[134:135]
	v_pk_add_f32 v[134:135], v[10:11], v[144:145]
	global_store_dwordx4 v[142:143], v[138:141], off
	global_store_dwordx4 v[142:143], v[134:137], off offset:16
	s_nop 0
	v_cvt_f32_f16_e32 v138, v132
	v_cvt_f32_f16_e32 v134, v130
	v_cvt_f32_f16_sdwa v135, v130 dst_sel:DWORD dst_unused:UNUSED_PAD src0_sel:WORD_1
	v_cvt_f32_f16_e32 v130, v131
	v_cvt_f32_f16_sdwa v131, v131 dst_sel:DWORD dst_unused:UNUSED_PAD src0_sel:WORD_1
	v_cvt_f32_f16_sdwa v139, v132 dst_sel:DWORD dst_unused:UNUSED_PAD src0_sel:WORD_1
	v_pk_add_f32 v[134:135], v[6:7], v[134:135]
	v_pk_add_f32 v[136:137], v[8:9], v[130:131]
	v_cvt_f32_f16_e32 v130, v133
	v_cvt_f32_f16_sdwa v131, v133 dst_sel:DWORD dst_unused:UNUSED_PAD src0_sel:WORD_1
	v_pk_add_f32 v[132:133], v[4:5], v[130:131]
	v_pk_add_f32 v[130:131], v[2:3], v[138:139]
	global_store_dwordx4 v[142:143], v[134:137], off offset:128
	global_store_dwordx4 v[142:143], v[130:133], off offset:144
	s_cbranch_execnz .LBB0_502
;     __device__ __forceinline__ void operator()(const f32x4 (&acc)[2][2][4][2], const pg8::Unit& u, int, LAS unsigned char*, int wr, int wc, int fr_, int fq_) const {
;     ...
;         if (layer == 0) {
; #pragma unroll
;             for (int ai = 0; ai < 2; ++ai) {
;                 f16x8 xh[4][2];
;                 float ssv[4];
; #pragma unroll
;                 for (int m = 0; m < 4; ++m)
; #pragma unroll
;                     for (int bj = 0; bj < 2; ++bj) xh[m][bj] = *(const f16x8*)(XH + (size_t)(row0 + ai * 128 + m * 16) * DM + col0 + bj * 32);
; #pragma unroll
;                 for (int m = 0; m < 4; ++m) {
;                     const int row = row0 + ai * 128 + m * 16;
;                     float ss = 0.f;
; #pragma unroll
;                     for (int bj = 0; bj < 2; ++bj) {
;                         f16x8 hv;
; #pragma unroll
;                         for (int e = 0; e < 8; ++e) { hv[e] = (f16)((float)xh[m][bj][e] + acc[ai][bj][m][e >> 2][e & 3]); const float tr = (float)hv[e]; ss += tr * tr; }
;                         *(f16x8*)(XH + (size_t)row * DM + col0 + bj * 32) = hv;
;                     }
;                     ss = sum_fq(ss);
;                     ssv[m] = ss;
;                 }
;                 const float s01 = (fq & 1) ? ssv[1] : ssv[0], s23 = (fq & 1) ? ssv[3] : ssv[2];
;                 SS[(size_t)(row0 + ai * 128 + fq * 16) * 16 + u.pn * 4 + wc] = (fq & 2) ? s23 : s01;
;             }
.LBB0_504:
	s_nop 0
	v_and_b32_e32 v130, 1, v234
	v_lshlrev_b64 v[160:161], 1, v[188:189]
	v_ashrrev_i32_e32 v187, 31, v186
	v_cmp_eq_u32_e32 vcc, 0, v130
	v_and_b32_e32 v130, 2, v234
	v_lshl_add_u64 v[162:163], s[40:41], 0, v[160:161]
	v_lshlrev_b64 v[164:165], 11, v[186:187]
	v_cmp_eq_u32_e64 s[0:1], 0, v130
	v_lshl_add_u64 v[130:131], v[162:163], 0, v[164:165]
	v_mov_b32_e32 v172, 0
	v_mov_b32_e32 v173, 0
	v_mov_b32_e32 v174, 0
	v_mov_b32_e32 v175, 0
	v_mov_b32_e32 v154, 0
	v_mov_b32_e32 v155, 0
	v_mov_b32_e32 v156, 0
	v_mov_b32_e32 v157, 0
	s_mov_b64 s[6:7], 0x8000
	v_lshl_add_u64 v[170:171], v[164:165], 0, s[6:7]
	v_lshl_add_u64 v[130:131], v[162:163], 0, v[170:171]
	v_mov_b32_e32 v150, 0
	v_mov_b32_e32 v151, 0
	v_mov_b32_e32 v152, 0
	v_mov_b32_e32 v153, 0
	v_mov_b32_e32 v146, 0
	v_mov_b32_e32 v147, 0
	v_mov_b32_e32 v148, 0
	v_mov_b32_e32 v149, 0
	s_mov_b64 s[6:7], 0x10000
	v_lshl_add_u64 v[168:169], v[164:165], 0, s[6:7]
	s_mov_b64 s[6:7], 0x18000
	v_lshl_add_u64 v[130:131], v[162:163], 0, v[168:169]
	v_lshl_add_u64 v[166:167], v[164:165], 0, s[6:7]
	v_mov_b32_e32 v142, 0
	v_mov_b32_e32 v143, 0
	v_mov_b32_e32 v144, 0
	v_mov_b32_e32 v145, 0
	v_mov_b32_e32 v138, 0
	v_mov_b32_e32 v139, 0
	v_mov_b32_e32 v140, 0
	v_mov_b32_e32 v141, 0
	v_lshl_add_u64 v[130:131], v[162:163], 0, v[166:167]
	v_mov_b32_e32 v134, 0
	v_mov_b32_e32 v135, 0
	v_mov_b32_e32 v136, 0
	v_mov_b32_e32 v137, 0
	s_nop 0
	v_mov_b32_e32 v130, 0
	v_mov_b32_e32 v131, 0
	v_mov_b32_e32 v132, 0
	v_mov_b32_e32 v133, 0
	v_lshl_add_u32 v158, v234, 4, v186
	s_lshl_b32 s72, s94, 2
	v_readlane_b32 s10, v254, 4
	s_ashr_i32 s73, s72, 31
	v_readlane_b32 s11, v254, 5
	s_lshl_b64 s[72:73], s[72:73], 2
	v_readlane_b32 s34, v254, 51
	v_readlane_b32 s35, v254, 52
	s_mov_b64 s[6:7], 0x40000
	v_cvt_f32_f16_e32 v159, v172
	v_cvt_f32_f16_sdwa v172, v172 dst_sel:DWORD dst_unused:UNUSED_PAD src0_sel:WORD_1
	v_add_f32_e32 v126, v126, v159
	v_add_f32_e32 v127, v127, v172
	v_cvt_f16_f32_e32 v172, v127
	v_cvt_f16_f32_e32 v159, v126
	v_cvt_pk_f16_f32 v126, v126, v127
	v_cvt_f32_f16_e32 v127, v172
	v_cvt_f32_f16_e32 v172, v173
	v_cvt_f32_f16_sdwa v173, v173 dst_sel:DWORD dst_unused:UNUSED_PAD src0_sel:WORD_1
	v_mul_f32_e32 v127, v127, v127
	v_fma_mix_f32 v159, v159, v159, v127 op_sel_hi:[1,1,0]
	v_pk_add_f32 v[128:129], v[128:129], v[172:173]
	s_nop 0
	v_cvt_pk_f16_f32 v127, v128, v129
	v_fma_mix_f32 v128, v127, v127, v159 op_sel_hi:[1,1,0]
	v_cvt_f32_f16_sdwa v129, v174 dst_sel:DWORD dst_unused:UNUSED_PAD src0_sel:WORD_1
	v_fma_mix_f32 v159, v127, v127, v128 op_sel:[1,1,0] op_sel_hi:[1,1,0]
	v_cvt_f32_f16_e32 v128, v174
	v_pk_add_f32 v[122:123], v[122:123], v[128:129]
	s_nop 0
	v_cvt_pk_f16_f32 v128, v122, v123
	v_fma_mix_f32 v122, v128, v128, v159 op_sel_hi:[1,1,0]
	v_cvt_f32_f16_sdwa v123, v175 dst_sel:DWORD dst_unused:UNUSED_PAD src0_sel:WORD_1
	v_fma_mix_f32 v159, v128, v128, v122 op_sel:[1,1,0] op_sel_hi:[1,1,0]
	v_cvt_f32_f16_e32 v122, v175
	v_pk_add_f32 v[122:123], v[124:125], v[122:123]
	v_cvt_f32_f16_e32 v125, v154
	v_cvt_pk_f16_f32 v129, v122, v123
	v_fma_mix_f32 v122, v129, v129, v159 op_sel_hi:[1,1,0]
	v_ashrrev_i32_e32 v159, 31, v158
	v_add_f32_e32 v118, v118, v125
	v_cvt_f16_f32_e32 v125, v118
	v_fma_mix_f32 v124, v129, v129, v122 op_sel:[1,1,0] op_sel_hi:[1,1,0]
	v_lshl_add_u64 v[122:123], s[40:41], 0, v[164:165]
	v_lshl_add_u64 v[122:123], v[122:123], 0, v[160:161]
	v_fma_mix_f32 v124, v125, v125, v124 op_sel_hi:[1,1,0]
	v_cvt_f32_f16_sdwa v125, v154 dst_sel:DWORD dst_unused:UNUSED_PAD src0_sel:WORD_1
	global_store_dwordx4 v[122:123], v[126:129], off
	v_add_f32_e32 v119, v119, v125
	v_cvt_f16_f32_e32 v125, v119
	v_cvt_pk_f16_f32 v118, v118, v119
	v_fma_mix_f32 v126, v125, v125, v124 op_sel_hi:[1,1,0]
	v_cvt_f32_f16_e32 v124, v155
	v_cvt_f32_f16_sdwa v125, v155 dst_sel:DWORD dst_unused:UNUSED_PAD src0_sel:WORD_1
	v_pk_add_f32 v[120:121], v[120:121], v[124:125]
	s_nop 0
	v_cvt_pk_f16_f32 v119, v120, v121
	v_fma_mix_f32 v120, v119, v119, v126 op_sel_hi:[1,1,0]
	v_cvt_f32_f16_sdwa v121, v156 dst_sel:DWORD dst_unused:UNUSED_PAD src0_sel:WORD_1
	v_fma_mix_f32 v124, v119, v119, v120 op_sel:[1,1,0] op_sel_hi:[1,1,0]
	v_cvt_f32_f16_e32 v120, v156
	v_pk_add_f32 v[114:115], v[114:115], v[120:121]
	s_nop 0
	v_cvt_pk_f16_f32 v120, v114, v115
	v_fma_mix_f32 v114, v120, v120, v124 op_sel_hi:[1,1,0]
	v_cvt_f32_f16_sdwa v115, v157 dst_sel:DWORD dst_unused:UNUSED_PAD src0_sel:WORD_1
	v_fma_mix_f32 v124, v120, v120, v114 op_sel:[1,1,0] op_sel_hi:[1,1,0]
	v_cvt_f32_f16_e32 v114, v157
	v_pk_add_f32 v[114:115], v[116:117], v[114:115]
	s_nop 0
	v_cvt_pk_f16_f32 v121, v114, v115
	v_fma_mix_f32 v114, v121, v121, v124 op_sel_hi:[1,1,0]
	v_cvt_f32_f16_sdwa v116, v150 dst_sel:DWORD dst_unused:UNUSED_PAD src0_sel:WORD_1
	v_fma_mix_f32 v114, v121, v121, v114 op_sel:[1,1,0] op_sel_hi:[1,1,0]
	v_cvt_f32_f16_sdwa v117, v151 dst_sel:DWORD dst_unused:UNUSED_PAD src0_sel:WORD_1
	v_mov_b32_e32 v115, v114
	s_nop 1
	v_permlane16_swap_b32_e32 v114, v115
	v_add_f32_e32 v114, v114, v115
	v_mov_b32_e32 v115, v114
	s_nop 1
	v_permlane32_swap_b32_e32 v114, v115
	v_add_f32_e32 v114, v114, v115
	v_cvt_f32_f16_e32 v115, v150
	v_add_f32_e32 v111, v111, v116
	v_cvt_f16_f32_e32 v116, v111
	global_store_dwordx4 v[122:123], v[118:121], off offset:64
	v_add_f32_e32 v110, v110, v115
	v_cvt_f16_f32_e32 v115, v110
	v_cvt_pk_f16_f32 v110, v110, v111
	v_cvt_f32_f16_e32 v111, v116
	v_cvt_f32_f16_e32 v116, v151
	v_mul_f32_e32 v111, v111, v111
	v_pk_add_f32 v[112:113], v[112:113], v[116:117]
	v_fma_mix_f32 v115, v115, v115, v111 op_sel_hi:[1,1,0]
	v_cvt_pk_f16_f32 v111, v112, v113
	v_fma_mix_f32 v112, v111, v111, v115 op_sel_hi:[1,1,0]
;     __device__ __forceinline__ void operator()(const f32x4 (&acc)[2][2][4][2], const pg8::Unit& u, int, LAS unsigned char*, int wr, int wc, int fr_, int fq_) const {
;     ...
;                 for (int m = 0; m < 4; ++m)
; #pragma unroll
;                     for (int bj = 0; bj < 2; ++bj) xh[m][bj] = *(const f16x8*)(XH + (size_t)(row0 + ai * 128 + m * 16) * DM + col0 + bj * 32);
; #pragma unroll
;                 for (int m = 0; m < 4; ++m) {
;                     const int row = row0 + ai * 128 + m * 16;
;                     float ss = 0.f;
; #pragma unroll
;                     for (int bj = 0; bj < 2; ++bj) {
;                         f16x8 hv;
; #pragma unroll
;                         for (int e = 0; e < 8; ++e) { hv[e] = (f16)((float)xh[m][bj][e] + acc[ai][bj][m][e >> 2][e & 3]); const float tr = (float)hv[e]; ss += tr * tr; }
;                         *(f16x8*)(XH + (size_t)row * DM + col0 + bj * 32) = hv;
;                     }
;                     ss = sum_fq(ss);
;                     ssv[m] = ss;
;                 }
	v_cvt_f32_f16_sdwa v113, v152 dst_sel:DWORD dst_unused:UNUSED_PAD src0_sel:WORD_1
	v_fma_mix_f32 v115, v111, v111, v112 op_sel:[1,1,0] op_sel_hi:[1,1,0]
	v_cvt_f32_f16_e32 v112, v152
	v_pk_add_f32 v[106:107], v[106:107], v[112:113]
	s_nop 0
	v_cvt_pk_f16_f32 v112, v106, v107
	v_fma_mix_f32 v106, v112, v112, v115 op_sel_hi:[1,1,0]
	v_cvt_f32_f16_sdwa v107, v153 dst_sel:DWORD dst_unused:UNUSED_PAD src0_sel:WORD_1
	v_fma_mix_f32 v115, v112, v112, v106 op_sel:[1,1,0] op_sel_hi:[1,1,0]
	v_cvt_f32_f16_e32 v106, v153
	v_pk_add_f32 v[106:107], v[108:109], v[106:107]
	v_cvt_f32_f16_e32 v109, v146
	v_cvt_pk_f16_f32 v113, v106, v107
	v_fma_mix_f32 v106, v113, v113, v115 op_sel_hi:[1,1,0]
	v_add_f32_e32 v102, v102, v109
	v_cvt_f16_f32_e32 v109, v102
	v_fma_mix_f32 v108, v113, v113, v106 op_sel:[1,1,0] op_sel_hi:[1,1,0]
	v_lshl_add_u64 v[106:107], s[40:41], 0, v[170:171]
	v_lshl_add_u64 v[106:107], v[106:107], 0, v[160:161]
	v_fma_mix_f32 v108, v109, v109, v108 op_sel_hi:[1,1,0]
	v_cvt_f32_f16_sdwa v109, v146 dst_sel:DWORD dst_unused:UNUSED_PAD src0_sel:WORD_1
	global_store_dwordx4 v[106:107], v[110:113], off
	v_add_f32_e32 v103, v103, v109
	v_cvt_f16_f32_e32 v109, v103
	v_cvt_pk_f16_f32 v102, v102, v103
	v_fma_mix_f32 v110, v109, v109, v108 op_sel_hi:[1,1,0]
	v_cvt_f32_f16_e32 v108, v147
	v_cvt_f32_f16_sdwa v109, v147 dst_sel:DWORD dst_unused:UNUSED_PAD src0_sel:WORD_1
	v_pk_add_f32 v[104:105], v[104:105], v[108:109]
	s_nop 0
	v_cvt_pk_f16_f32 v103, v104, v105
	v_fma_mix_f32 v104, v103, v103, v110 op_sel_hi:[1,1,0]
	v_cvt_f32_f16_sdwa v105, v148 dst_sel:DWORD dst_unused:UNUSED_PAD src0_sel:WORD_1
	v_fma_mix_f32 v108, v103, v103, v104 op_sel:[1,1,0] op_sel_hi:[1,1,0]
	v_cvt_f32_f16_e32 v104, v148
	v_pk_add_f32 v[98:99], v[98:99], v[104:105]
	s_nop 0
	v_cvt_pk_f16_f32 v104, v98, v99
	v_fma_mix_f32 v98, v104, v104, v108 op_sel_hi:[1,1,0]
	v_cvt_f32_f16_sdwa v99, v149 dst_sel:DWORD dst_unused:UNUSED_PAD src0_sel:WORD_1
	v_fma_mix_f32 v108, v104, v104, v98 op_sel:[1,1,0] op_sel_hi:[1,1,0]
	v_cvt_f32_f16_e32 v98, v149
	v_pk_add_f32 v[98:99], v[100:101], v[98:99]
	s_nop 0
	v_cvt_pk_f16_f32 v105, v98, v99
	v_fma_mix_f32 v98, v105, v105, v108 op_sel_hi:[1,1,0]
	v_cvt_f32_f16_sdwa v100, v142 dst_sel:DWORD dst_unused:UNUSED_PAD src0_sel:WORD_1
	v_fma_mix_f32 v98, v105, v105, v98 op_sel:[1,1,0] op_sel_hi:[1,1,0]
	v_cvt_f32_f16_sdwa v101, v143 dst_sel:DWORD dst_unused:UNUSED_PAD src0_sel:WORD_1
	v_mov_b32_e32 v99, v98
	s_nop 1
	v_permlane16_swap_b32_e32 v98, v99
	v_add_f32_e32 v98, v98, v99
	v_mov_b32_e32 v99, v98
	s_nop 1
	v_permlane32_swap_b32_e32 v98, v99
	v_add_f32_e32 v98, v98, v99
	v_cvt_f32_f16_e32 v99, v142
	v_add_f32_e32 v95, v95, v100
	v_cvt_f16_f32_e32 v100, v95
	global_store_dwordx4 v[106:107], v[102:105], off offset:64
	v_add_f32_e32 v94, v94, v99
	v_cvt_f16_f32_e32 v99, v94
	v_cvt_pk_f16_f32 v94, v94, v95
	v_cvt_f32_f16_e32 v95, v100
	v_cvt_f32_f16_e32 v100, v143
	v_lshl_add_u64 v[104:105], v[164:165], 0, s[6:7]
	s_mov_b64 s[6:7], 0x48000
	v_mul_f32_e32 v95, v95, v95
	v_pk_add_f32 v[96:97], v[96:97], v[100:101]
	v_fma_mix_f32 v99, v99, v99, v95 op_sel_hi:[1,1,0]
	v_cvt_pk_f16_f32 v95, v96, v97
	v_fma_mix_f32 v96, v95, v95, v99 op_sel_hi:[1,1,0]
	v_cvt_f32_f16_sdwa v97, v144 dst_sel:DWORD dst_unused:UNUSED_PAD src0_sel:WORD_1
	v_fma_mix_f32 v99, v95, v95, v96 op_sel:[1,1,0] op_sel_hi:[1,1,0]
	v_cvt_f32_f16_e32 v96, v144
	v_pk_add_f32 v[90:91], v[90:91], v[96:97]
	s_nop 0
	v_cvt_pk_f16_f32 v96, v90, v91
	v_fma_mix_f32 v90, v96, v96, v99 op_sel_hi:[1,1,0]
	v_cvt_f32_f16_sdwa v91, v145 dst_sel:DWORD dst_unused:UNUSED_PAD src0_sel:WORD_1
	v_fma_mix_f32 v99, v96, v96, v90 op_sel:[1,1,0] op_sel_hi:[1,1,0]
	v_cvt_f32_f16_e32 v90, v145
	v_pk_add_f32 v[90:91], v[92:93], v[90:91]
	v_cvt_f32_f16_e32 v93, v138
	v_cvt_pk_f16_f32 v97, v90, v91
	v_fma_mix_f32 v90, v97, v97, v99 op_sel_hi:[1,1,0]
	v_add_f32_e32 v86, v86, v93
	v_cvt_f16_f32_e32 v93, v86
	v_fma_mix_f32 v92, v97, v97, v90 op_sel:[1,1,0] op_sel_hi:[1,1,0]
	v_lshl_add_u64 v[90:91], s[40:41], 0, v[168:169]
	v_lshl_add_u64 v[90:91], v[90:91], 0, v[160:161]
	v_fma_mix_f32 v92, v93, v93, v92 op_sel_hi:[1,1,0]
	v_cvt_f32_f16_sdwa v93, v138 dst_sel:DWORD dst_unused:UNUSED_PAD src0_sel:WORD_1
	global_store_dwordx4 v[90:91], v[94:97], off
	v_add_f32_e32 v87, v87, v93
	v_cvt_f16_f32_e32 v93, v87
	v_cvt_pk_f16_f32 v86, v86, v87
	v_fma_mix_f32 v94, v93, v93, v92 op_sel_hi:[1,1,0]
	v_cvt_f32_f16_e32 v92, v139
	v_cvt_f32_f16_sdwa v93, v139 dst_sel:DWORD dst_unused:UNUSED_PAD src0_sel:WORD_1
	v_pk_add_f32 v[88:89], v[88:89], v[92:93]
	s_nop 0
	v_cvt_pk_f16_f32 v87, v88, v89
	v_fma_mix_f32 v88, v87, v87, v94 op_sel_hi:[1,1,0]
	v_cvt_f32_f16_sdwa v89, v140 dst_sel:DWORD dst_unused:UNUSED_PAD src0_sel:WORD_1
	v_fma_mix_f32 v92, v87, v87, v88 op_sel:[1,1,0] op_sel_hi:[1,1,0]
	v_cvt_f32_f16_e32 v88, v140
	v_pk_add_f32 v[82:83], v[82:83], v[88:89]
	s_nop 0
	v_cvt_pk_f16_f32 v88, v82, v83
	v_fma_mix_f32 v82, v88, v88, v92 op_sel_hi:[1,1,0]
	v_cvt_f32_f16_sdwa v83, v141 dst_sel:DWORD dst_unused:UNUSED_PAD src0_sel:WORD_1
	v_fma_mix_f32 v92, v88, v88, v82 op_sel:[1,1,0] op_sel_hi:[1,1,0]
	v_cvt_f32_f16_e32 v82, v141
	v_pk_add_f32 v[82:83], v[84:85], v[82:83]
	s_nop 0
	v_cvt_pk_f16_f32 v89, v82, v83
	v_fma_mix_f32 v82, v89, v89, v92 op_sel_hi:[1,1,0]
	global_store_dwordx4 v[90:91], v[86:89], off offset:64
	v_fma_mix_f32 v82, v89, v89, v82 op_sel:[1,1,0] op_sel_hi:[1,1,0]
	s_nop 0
	v_mov_b32_e32 v83, v82
	s_nop 1
	v_permlane16_swap_b32_e32 v82, v83
	v_add_f32_e32 v82, v82, v83
	v_mov_b32_e32 v83, v82
	s_nop 1
	v_permlane32_swap_b32_e32 v82, v83
	v_add_f32_e32 v84, v82, v83
	v_cvt_f32_f16_sdwa v83, v134 dst_sel:DWORD dst_unused:UNUSED_PAD src0_sel:WORD_1
;     __device__ __forceinline__ void operator()(const f32x4 (&acc)[2][2][4][2], const pg8::Unit& u, int, LAS unsigned char*, int wr, int wc, int fr_, int fq_) const {
;     ...
;                 for (int m = 0; m < 4; ++m)
; #pragma unroll
;                     for (int bj = 0; bj < 2; ++bj) xh[m][bj] = *(const f16x8*)(XH + (size_t)(row0 + ai * 128 + m * 16) * DM + col0 + bj * 32);
; #pragma unroll
;                 for (int m = 0; m < 4; ++m) {
;                     const int row = row0 + ai * 128 + m * 16;
;                     float ss = 0.f;
; #pragma unroll
;                     for (int bj = 0; bj < 2; ++bj) {
;                         f16x8 hv;
; #pragma unroll
;                         for (int e = 0; e < 8; ++e) { hv[e] = (f16)((float)xh[m][bj][e] + acc[ai][bj][m][e >> 2][e & 3]); const float tr = (float)hv[e]; ss += tr * tr; }
;                         *(f16x8*)(XH + (size_t)row * DM + col0 + bj * 32) = hv;
;                     }
;                     ss = sum_fq(ss);
;                     ssv[m] = ss;
;                 }
;                 const float s01 = (fq & 1) ? ssv[1] : ssv[0], s23 = (fq & 1) ? ssv[3] : ssv[2];
;                 SS[(size_t)(row0 + ai * 128 + fq * 16) * 16 + u.pn * 4 + wc] = (fq & 2) ? s23 : s01;
	v_cvt_f32_f16_e32 v82, v134
	v_add_f32_e32 v79, v79, v83
	v_cvt_f16_f32_e32 v83, v79
	v_add_f32_e32 v78, v78, v82
	v_cvt_f16_f32_e32 v82, v78
	v_cvt_pk_f16_f32 v78, v78, v79
	v_cvt_f32_f16_e32 v79, v83
	v_cvt_f32_f16_sdwa v83, v135 dst_sel:DWORD dst_unused:UNUSED_PAD src0_sel:WORD_1
	v_mul_f32_e32 v79, v79, v79
	v_fma_mix_f32 v85, v82, v82, v79 op_sel_hi:[1,1,0]
	v_cvt_f32_f16_e32 v82, v135
	v_pk_add_f32 v[80:81], v[80:81], v[82:83]
	s_nop 0
	v_cvt_pk_f16_f32 v79, v80, v81
	v_fma_mix_f32 v80, v79, v79, v85 op_sel_hi:[1,1,0]
	v_cvt_f32_f16_sdwa v81, v136 dst_sel:DWORD dst_unused:UNUSED_PAD src0_sel:WORD_1
	v_fma_mix_f32 v82, v79, v79, v80 op_sel:[1,1,0] op_sel_hi:[1,1,0]
	v_cvt_f32_f16_e32 v80, v136
	v_pk_add_f32 v[74:75], v[74:75], v[80:81]
	s_nop 0
	v_cvt_pk_f16_f32 v80, v74, v75
	v_fma_mix_f32 v74, v80, v80, v82 op_sel_hi:[1,1,0]
	v_cvt_f32_f16_sdwa v75, v137 dst_sel:DWORD dst_unused:UNUSED_PAD src0_sel:WORD_1
	v_fma_mix_f32 v82, v80, v80, v74 op_sel:[1,1,0] op_sel_hi:[1,1,0]
	v_cvt_f32_f16_e32 v74, v137
	v_pk_add_f32 v[74:75], v[76:77], v[74:75]
	v_cvt_f32_f16_e32 v77, v130
	v_cvt_pk_f16_f32 v81, v74, v75
	v_fma_mix_f32 v74, v81, v81, v82 op_sel_hi:[1,1,0]
	v_add_f32_e32 v70, v70, v77
	v_cvt_f16_f32_e32 v77, v70
	v_fma_mix_f32 v76, v81, v81, v74 op_sel:[1,1,0] op_sel_hi:[1,1,0]
	v_lshl_add_u64 v[74:75], s[40:41], 0, v[166:167]
	v_lshl_add_u64 v[74:75], v[74:75], 0, v[160:161]
	v_fma_mix_f32 v76, v77, v77, v76 op_sel_hi:[1,1,0]
	v_cvt_f32_f16_sdwa v77, v130 dst_sel:DWORD dst_unused:UNUSED_PAD src0_sel:WORD_1
	global_store_dwordx4 v[74:75], v[78:81], off
	v_add_f32_e32 v71, v71, v77
	v_cvt_f16_f32_e32 v77, v71
	v_cvt_pk_f16_f32 v70, v70, v71
	v_fma_mix_f32 v78, v77, v77, v76 op_sel_hi:[1,1,0]
	v_cvt_f32_f16_e32 v76, v131
	v_cvt_f32_f16_sdwa v77, v131 dst_sel:DWORD dst_unused:UNUSED_PAD src0_sel:WORD_1
	v_pk_add_f32 v[72:73], v[72:73], v[76:77]
	s_nop 0
	v_cvt_pk_f16_f32 v71, v72, v73
	v_fma_mix_f32 v72, v71, v71, v78 op_sel_hi:[1,1,0]
	v_cvt_f32_f16_sdwa v73, v132 dst_sel:DWORD dst_unused:UNUSED_PAD src0_sel:WORD_1
	v_fma_mix_f32 v76, v71, v71, v72 op_sel:[1,1,0] op_sel_hi:[1,1,0]
	v_cvt_f32_f16_e32 v72, v132
	v_pk_add_f32 v[66:67], v[66:67], v[72:73]
	s_nop 0
	v_cvt_pk_f16_f32 v72, v66, v67
	v_fma_mix_f32 v66, v72, v72, v76 op_sel_hi:[1,1,0]
	v_cvt_f32_f16_sdwa v67, v133 dst_sel:DWORD dst_unused:UNUSED_PAD src0_sel:WORD_1
	v_fma_mix_f32 v76, v72, v72, v66 op_sel:[1,1,0] op_sel_hi:[1,1,0]
	v_cvt_f32_f16_e32 v66, v133
	v_pk_add_f32 v[66:67], v[68:69], v[66:67]
	s_nop 0
	v_cvt_pk_f16_f32 v73, v66, v67
	v_fma_mix_f32 v66, v73, v73, v76 op_sel_hi:[1,1,0]
	global_store_dwordx4 v[74:75], v[70:73], off offset:64
	v_fma_mix_f32 v66, v73, v73, v66 op_sel:[1,1,0] op_sel_hi:[1,1,0]
	s_nop 0
	v_mov_b32_e32 v67, v66
	s_nop 1
	v_permlane16_swap_b32_e32 v66, v67
	v_add_f32_e32 v66, v66, v67
	v_mov_b32_e32 v67, v66
	s_nop 1
	v_permlane32_swap_b32_e32 v66, v67
	v_add_f32_e32 v66, v66, v67
	v_cndmask_b32_e32 v67, v98, v114, vcc
	v_cndmask_b32_e32 v66, v66, v84, vcc
	v_cndmask_b32_e64 v68, v66, v67, s[0:1]
	v_lshlrev_b64 v[66:67], 6, v[158:159]
	v_lshl_add_u64 v[66:67], s[10:11], 0, v[66:67]
	v_lshl_add_u64 v[66:67], v[66:67], 0, s[72:73]
	v_lshl_add_u64 v[66:67], v[66:67], 0, s[34:35]
	global_store_dword v[66:67], v68, off
	v_lshl_add_u64 v[66:67], v[162:163], 0, v[104:105]
	v_mov_b32_e32 v100, 0
	v_mov_b32_e32 v101, 0
	v_mov_b32_e32 v102, 0
	v_mov_b32_e32 v103, 0
	v_mov_b32_e32 v90, 0
	v_mov_b32_e32 v91, 0
	v_mov_b32_e32 v92, 0
	v_mov_b32_e32 v93, 0
	v_lshl_add_u64 v[98:99], v[164:165], 0, s[6:7]
	v_lshl_add_u64 v[66:67], v[162:163], 0, v[98:99]
	v_mov_b32_e32 v86, 0
	v_mov_b32_e32 v87, 0
	v_mov_b32_e32 v88, 0
	v_mov_b32_e32 v89, 0
	v_mov_b32_e32 v82, 0
	v_mov_b32_e32 v83, 0
	v_mov_b32_e32 v84, 0
	v_mov_b32_e32 v85, 0
	s_mov_b64 s[6:7], 0x50000
	v_lshl_add_u64 v[96:97], v[164:165], 0, s[6:7]
	s_mov_b64 s[6:7], 0x58000
	v_lshl_add_u64 v[66:67], v[162:163], 0, v[96:97]
	v_lshl_add_u64 v[94:95], v[164:165], 0, s[6:7]
	v_mov_b32_e32 v78, 0
	v_mov_b32_e32 v79, 0
	v_mov_b32_e32 v80, 0
	v_mov_b32_e32 v81, 0
	v_mov_b32_e32 v74, 0
	v_mov_b32_e32 v75, 0
	v_mov_b32_e32 v76, 0
	v_mov_b32_e32 v77, 0
	v_lshl_add_u64 v[66:67], v[162:163], 0, v[94:95]
	v_mov_b32_e32 v70, 0
	v_mov_b32_e32 v71, 0
	v_mov_b32_e32 v72, 0
	v_mov_b32_e32 v73, 0
	s_nop 0
	v_mov_b32_e32 v66, 0
	v_mov_b32_e32 v67, 0
	v_mov_b32_e32 v68, 0
	v_mov_b32_e32 v69, 0
	v_cvt_f32_f16_e32 v106, v100
	v_cvt_f32_f16_sdwa v100, v100 dst_sel:DWORD dst_unused:UNUSED_PAD src0_sel:WORD_1
	v_add_f32_e32 v62, v62, v106
	v_add_f32_e32 v63, v63, v100
	v_cvt_f16_f32_e32 v100, v63
	v_cvt_f16_f32_e32 v106, v62
	v_cvt_pk_f16_f32 v62, v62, v63
	v_cvt_f32_f16_e32 v63, v100
	v_cvt_f32_f16_e32 v100, v101
	v_cvt_f32_f16_sdwa v101, v101 dst_sel:DWORD dst_unused:UNUSED_PAD src0_sel:WORD_1
	v_mul_f32_e32 v63, v63, v63
	v_fma_mix_f32 v106, v106, v106, v63 op_sel_hi:[1,1,0]
	v_pk_add_f32 v[64:65], v[64:65], v[100:101]
	s_nop 0
	v_cvt_pk_f16_f32 v63, v64, v65
	v_fma_mix_f32 v64, v63, v63, v106 op_sel_hi:[1,1,0]
	v_cvt_f32_f16_sdwa v65, v102 dst_sel:DWORD dst_unused:UNUSED_PAD src0_sel:WORD_1
	v_fma_mix_f32 v100, v63, v63, v64 op_sel:[1,1,0] op_sel_hi:[1,1,0]
	v_cvt_f32_f16_e32 v64, v102
	v_pk_add_f32 v[58:59], v[58:59], v[64:65]
	s_nop 0
	v_cvt_pk_f16_f32 v64, v58, v59
	v_fma_mix_f32 v58, v64, v64, v100 op_sel_hi:[1,1,0]
	v_cvt_f32_f16_sdwa v59, v103 dst_sel:DWORD dst_unused:UNUSED_PAD src0_sel:WORD_1
	v_fma_mix_f32 v100, v64, v64, v58 op_sel:[1,1,0] op_sel_hi:[1,1,0]
	v_cvt_f32_f16_e32 v58, v103
	v_pk_add_f32 v[58:59], v[60:61], v[58:59]
	v_cvt_f32_f16_e32 v61, v90
	v_cvt_pk_f16_f32 v65, v58, v59
	v_fma_mix_f32 v58, v65, v65, v100 op_sel_hi:[1,1,0]
;     __device__ __forceinline__ void operator()(const f32x4 (&acc)[2][2][4][2], const pg8::Unit& u, int, LAS unsigned char*, int wr, int wc, int fr_, int fq_) const {
;     ...
;                 for (int m = 0; m < 4; ++m)
; #pragma unroll
;                     for (int bj = 0; bj < 2; ++bj) xh[m][bj] = *(const f16x8*)(XH + (size_t)(row0 + ai * 128 + m * 16) * DM + col0 + bj * 32);
; #pragma unroll
;                 for (int m = 0; m < 4; ++m) {
;                     const int row = row0 + ai * 128 + m * 16;
;                     float ss = 0.f;
; #pragma unroll
;                     for (int bj = 0; bj < 2; ++bj) {
;                         f16x8 hv;
; #pragma unroll
;                         for (int e = 0; e < 8; ++e) { hv[e] = (f16)((float)xh[m][bj][e] + acc[ai][bj][m][e >> 2][e & 3]); const float tr = (float)hv[e]; ss += tr * tr; }
;                         *(f16x8*)(XH + (size_t)row * DM + col0 + bj * 32) = hv;
;                     }
;                     ss = sum_fq(ss);
;                     ssv[m] = ss;
;                 }
	v_add_f32_e32 v54, v54, v61
	v_cvt_f16_f32_e32 v61, v54
	v_fma_mix_f32 v60, v65, v65, v58 op_sel:[1,1,0] op_sel_hi:[1,1,0]
	v_lshl_add_u64 v[58:59], s[40:41], 0, v[104:105]
	v_lshl_add_u64 v[58:59], v[58:59], 0, v[160:161]
	v_fma_mix_f32 v60, v61, v61, v60 op_sel_hi:[1,1,0]
	v_cvt_f32_f16_sdwa v61, v90 dst_sel:DWORD dst_unused:UNUSED_PAD src0_sel:WORD_1
	global_store_dwordx4 v[58:59], v[62:65], off
	v_add_f32_e32 v55, v55, v61
	v_cvt_f16_f32_e32 v61, v55
	v_cvt_pk_f16_f32 v54, v54, v55
	v_fma_mix_f32 v62, v61, v61, v60 op_sel_hi:[1,1,0]
	v_cvt_f32_f16_e32 v60, v91
	v_cvt_f32_f16_sdwa v61, v91 dst_sel:DWORD dst_unused:UNUSED_PAD src0_sel:WORD_1
	v_pk_add_f32 v[56:57], v[56:57], v[60:61]
	s_nop 0
	v_cvt_pk_f16_f32 v55, v56, v57
	v_fma_mix_f32 v56, v55, v55, v62 op_sel_hi:[1,1,0]
	v_cvt_f32_f16_sdwa v57, v92 dst_sel:DWORD dst_unused:UNUSED_PAD src0_sel:WORD_1
	v_fma_mix_f32 v60, v55, v55, v56 op_sel:[1,1,0] op_sel_hi:[1,1,0]
	v_cvt_f32_f16_e32 v56, v92
	v_pk_add_f32 v[50:51], v[50:51], v[56:57]
	s_nop 0
	v_cvt_pk_f16_f32 v56, v50, v51
	v_fma_mix_f32 v50, v56, v56, v60 op_sel_hi:[1,1,0]
	v_cvt_f32_f16_sdwa v51, v93 dst_sel:DWORD dst_unused:UNUSED_PAD src0_sel:WORD_1
	v_fma_mix_f32 v60, v56, v56, v50 op_sel:[1,1,0] op_sel_hi:[1,1,0]
	v_cvt_f32_f16_e32 v50, v93
	v_pk_add_f32 v[50:51], v[52:53], v[50:51]
	s_nop 0
	v_cvt_pk_f16_f32 v57, v50, v51
	v_fma_mix_f32 v50, v57, v57, v60 op_sel_hi:[1,1,0]
	v_cvt_f32_f16_sdwa v52, v86 dst_sel:DWORD dst_unused:UNUSED_PAD src0_sel:WORD_1
	v_fma_mix_f32 v50, v57, v57, v50 op_sel:[1,1,0] op_sel_hi:[1,1,0]
	v_cvt_f32_f16_sdwa v53, v87 dst_sel:DWORD dst_unused:UNUSED_PAD src0_sel:WORD_1
	v_mov_b32_e32 v51, v50
	s_nop 1
	v_permlane16_swap_b32_e32 v50, v51
	v_add_f32_e32 v50, v50, v51
	v_mov_b32_e32 v51, v50
	s_nop 1
	v_permlane32_swap_b32_e32 v50, v51
	v_add_f32_e32 v50, v50, v51
	v_cvt_f32_f16_e32 v51, v86
	v_add_f32_e32 v47, v47, v52
	v_cvt_f16_f32_e32 v52, v47
	global_store_dwordx4 v[58:59], v[54:57], off offset:64
	v_add_f32_e32 v46, v46, v51
	v_cvt_f16_f32_e32 v51, v46
	v_cvt_pk_f16_f32 v46, v46, v47
	v_cvt_f32_f16_e32 v47, v52
	v_cvt_f32_f16_e32 v52, v87
	v_mul_f32_e32 v47, v47, v47
	v_pk_add_f32 v[48:49], v[48:49], v[52:53]
	v_fma_mix_f32 v51, v51, v51, v47 op_sel_hi:[1,1,0]
	v_cvt_pk_f16_f32 v47, v48, v49
	v_fma_mix_f32 v48, v47, v47, v51 op_sel_hi:[1,1,0]
	v_cvt_f32_f16_sdwa v49, v88 dst_sel:DWORD dst_unused:UNUSED_PAD src0_sel:WORD_1
	v_fma_mix_f32 v51, v47, v47, v48 op_sel:[1,1,0] op_sel_hi:[1,1,0]
	v_cvt_f32_f16_e32 v48, v88
	v_pk_add_f32 v[42:43], v[42:43], v[48:49]
	s_nop 0
	v_cvt_pk_f16_f32 v48, v42, v43
	v_fma_mix_f32 v42, v48, v48, v51 op_sel_hi:[1,1,0]
	v_cvt_f32_f16_sdwa v43, v89 dst_sel:DWORD dst_unused:UNUSED_PAD src0_sel:WORD_1
	v_fma_mix_f32 v51, v48, v48, v42 op_sel:[1,1,0] op_sel_hi:[1,1,0]
	v_cvt_f32_f16_e32 v42, v89
	v_pk_add_f32 v[42:43], v[44:45], v[42:43]
	v_cvt_f32_f16_e32 v45, v82
	v_cvt_pk_f16_f32 v49, v42, v43
	v_fma_mix_f32 v42, v49, v49, v51 op_sel_hi:[1,1,0]
	v_add_f32_e32 v38, v38, v45
	v_cvt_f16_f32_e32 v45, v38
	v_fma_mix_f32 v44, v49, v49, v42 op_sel:[1,1,0] op_sel_hi:[1,1,0]
	v_lshl_add_u64 v[42:43], s[40:41], 0, v[98:99]
	v_lshl_add_u64 v[42:43], v[42:43], 0, v[160:161]
	v_fma_mix_f32 v44, v45, v45, v44 op_sel_hi:[1,1,0]
	v_cvt_f32_f16_sdwa v45, v82 dst_sel:DWORD dst_unused:UNUSED_PAD src0_sel:WORD_1
	global_store_dwordx4 v[42:43], v[46:49], off
	v_add_f32_e32 v39, v39, v45
	v_cvt_f16_f32_e32 v45, v39
	v_cvt_pk_f16_f32 v38, v38, v39
	v_fma_mix_f32 v46, v45, v45, v44 op_sel_hi:[1,1,0]
	v_cvt_f32_f16_e32 v44, v83
	v_cvt_f32_f16_sdwa v45, v83 dst_sel:DWORD dst_unused:UNUSED_PAD src0_sel:WORD_1
	v_pk_add_f32 v[40:41], v[40:41], v[44:45]
	s_nop 0
	v_cvt_pk_f16_f32 v39, v40, v41
	v_fma_mix_f32 v40, v39, v39, v46 op_sel_hi:[1,1,0]
	v_cvt_f32_f16_sdwa v41, v84 dst_sel:DWORD dst_unused:UNUSED_PAD src0_sel:WORD_1
	v_fma_mix_f32 v44, v39, v39, v40 op_sel:[1,1,0] op_sel_hi:[1,1,0]
	v_cvt_f32_f16_e32 v40, v84
	v_pk_add_f32 v[34:35], v[34:35], v[40:41]
	s_nop 0
	v_cvt_pk_f16_f32 v40, v34, v35
	v_fma_mix_f32 v34, v40, v40, v44 op_sel_hi:[1,1,0]
	v_cvt_f32_f16_sdwa v35, v85 dst_sel:DWORD dst_unused:UNUSED_PAD src0_sel:WORD_1
	v_fma_mix_f32 v44, v40, v40, v34 op_sel:[1,1,0] op_sel_hi:[1,1,0]
	v_cvt_f32_f16_e32 v34, v85
	v_pk_add_f32 v[34:35], v[36:37], v[34:35]
	s_nop 0
	v_cvt_pk_f16_f32 v41, v34, v35
	v_fma_mix_f32 v34, v41, v41, v44 op_sel_hi:[1,1,0]
	v_cvt_f32_f16_sdwa v36, v78 dst_sel:DWORD dst_unused:UNUSED_PAD src0_sel:WORD_1
	v_fma_mix_f32 v34, v41, v41, v34 op_sel:[1,1,0] op_sel_hi:[1,1,0]
	v_cvt_f32_f16_sdwa v37, v79 dst_sel:DWORD dst_unused:UNUSED_PAD src0_sel:WORD_1
	v_mov_b32_e32 v35, v34
	s_nop 1
	v_permlane16_swap_b32_e32 v34, v35
	v_add_f32_e32 v34, v34, v35
	v_mov_b32_e32 v35, v34
	s_nop 1
	v_permlane32_swap_b32_e32 v34, v35
	v_add_f32_e32 v34, v34, v35
	v_cvt_f32_f16_e32 v35, v78
	v_add_f32_e32 v31, v31, v36
	v_cvt_f16_f32_e32 v36, v31
	global_store_dwordx4 v[42:43], v[38:41], off offset:64
	v_add_f32_e32 v30, v30, v35
	v_cvt_f16_f32_e32 v35, v30
	v_cvt_pk_f16_f32 v30, v30, v31
	v_cvt_f32_f16_e32 v31, v36
	v_cvt_f32_f16_e32 v36, v79
	v_mul_f32_e32 v31, v31, v31
	v_pk_add_f32 v[32:33], v[32:33], v[36:37]
	v_fma_mix_f32 v35, v35, v35, v31 op_sel_hi:[1,1,0]
	v_cvt_pk_f16_f32 v31, v32, v33
	v_fma_mix_f32 v32, v31, v31, v35 op_sel_hi:[1,1,0]
	v_cvt_f32_f16_sdwa v33, v80 dst_sel:DWORD dst_unused:UNUSED_PAD src0_sel:WORD_1
	v_fma_mix_f32 v35, v31, v31, v32 op_sel:[1,1,0] op_sel_hi:[1,1,0]
	v_cvt_f32_f16_e32 v32, v80
	v_pk_add_f32 v[26:27], v[26:27], v[32:33]
;     __device__ __forceinline__ void operator()(const f32x4 (&acc)[2][2][4][2], const pg8::Unit& u, int, LAS unsigned char*, int wr, int wc, int fr_, int fq_) const {
;     ...
;                 for (int m = 0; m < 4; ++m)
; #pragma unroll
;                     for (int bj = 0; bj < 2; ++bj) xh[m][bj] = *(const f16x8*)(XH + (size_t)(row0 + ai * 128 + m * 16) * DM + col0 + bj * 32);
; #pragma unroll
;                 for (int m = 0; m < 4; ++m) {
;                     const int row = row0 + ai * 128 + m * 16;
;                     float ss = 0.f;
; #pragma unroll
;                     for (int bj = 0; bj < 2; ++bj) {
;                         f16x8 hv;
; #pragma unroll
;                         for (int e = 0; e < 8; ++e) { hv[e] = (f16)((float)xh[m][bj][e] + acc[ai][bj][m][e >> 2][e & 3]); const float tr = (float)hv[e]; ss += tr * tr; }
;                         *(f16x8*)(XH + (size_t)row * DM + col0 + bj * 32) = hv;
;                     }
;                     ss = sum_fq(ss);
;                     ssv[m] = ss;
;                 }
;                 const float s01 = (fq & 1) ? ssv[1] : ssv[0], s23 = (fq & 1) ? ssv[3] : ssv[2];
;                 SS[(size_t)(row0 + ai * 128 + fq * 16) * 16 + u.pn * 4 + wc] = (fq & 2) ? s23 : s01;
;             }
	s_nop 0
	v_cvt_pk_f16_f32 v32, v26, v27
	v_fma_mix_f32 v26, v32, v32, v35 op_sel_hi:[1,1,0]
	v_cvt_f32_f16_sdwa v27, v81 dst_sel:DWORD dst_unused:UNUSED_PAD src0_sel:WORD_1
	v_fma_mix_f32 v35, v32, v32, v26 op_sel:[1,1,0] op_sel_hi:[1,1,0]
	v_cvt_f32_f16_e32 v26, v81
	v_pk_add_f32 v[26:27], v[28:29], v[26:27]
	v_cvt_f32_f16_e32 v29, v74
	v_cvt_pk_f16_f32 v33, v26, v27
	v_fma_mix_f32 v26, v33, v33, v35 op_sel_hi:[1,1,0]
	v_add_f32_e32 v22, v22, v29
	v_cvt_f16_f32_e32 v29, v22
	v_fma_mix_f32 v28, v33, v33, v26 op_sel:[1,1,0] op_sel_hi:[1,1,0]
	v_lshl_add_u64 v[26:27], s[40:41], 0, v[96:97]
	v_lshl_add_u64 v[26:27], v[26:27], 0, v[160:161]
	v_fma_mix_f32 v28, v29, v29, v28 op_sel_hi:[1,1,0]
	v_cvt_f32_f16_sdwa v29, v74 dst_sel:DWORD dst_unused:UNUSED_PAD src0_sel:WORD_1
	global_store_dwordx4 v[26:27], v[30:33], off
	v_add_f32_e32 v23, v23, v29
	v_cvt_f16_f32_e32 v29, v23
	v_cvt_pk_f16_f32 v22, v22, v23
	v_fma_mix_f32 v30, v29, v29, v28 op_sel_hi:[1,1,0]
	v_cvt_f32_f16_e32 v28, v75
	v_cvt_f32_f16_sdwa v29, v75 dst_sel:DWORD dst_unused:UNUSED_PAD src0_sel:WORD_1
	v_pk_add_f32 v[24:25], v[24:25], v[28:29]
	s_nop 0
	v_cvt_pk_f16_f32 v23, v24, v25
	v_fma_mix_f32 v24, v23, v23, v30 op_sel_hi:[1,1,0]
	v_cvt_f32_f16_sdwa v25, v76 dst_sel:DWORD dst_unused:UNUSED_PAD src0_sel:WORD_1
	v_fma_mix_f32 v28, v23, v23, v24 op_sel:[1,1,0] op_sel_hi:[1,1,0]
	v_cvt_f32_f16_e32 v24, v76
	v_pk_add_f32 v[18:19], v[18:19], v[24:25]
	s_nop 0
	v_cvt_pk_f16_f32 v24, v18, v19
	v_fma_mix_f32 v18, v24, v24, v28 op_sel_hi:[1,1,0]
	v_cvt_f32_f16_sdwa v19, v77 dst_sel:DWORD dst_unused:UNUSED_PAD src0_sel:WORD_1
	v_fma_mix_f32 v28, v24, v24, v18 op_sel:[1,1,0] op_sel_hi:[1,1,0]
	v_cvt_f32_f16_e32 v18, v77
	v_pk_add_f32 v[18:19], v[20:21], v[18:19]
	s_nop 0
	v_cvt_pk_f16_f32 v25, v18, v19
	v_fma_mix_f32 v18, v25, v25, v28 op_sel_hi:[1,1,0]
	global_store_dwordx4 v[26:27], v[22:25], off offset:64
	v_fma_mix_f32 v18, v25, v25, v18 op_sel:[1,1,0] op_sel_hi:[1,1,0]
	s_nop 0
	v_mov_b32_e32 v19, v18
	s_nop 1
	v_permlane16_swap_b32_e32 v18, v19
	v_add_f32_e32 v18, v18, v19
	v_mov_b32_e32 v19, v18
	s_nop 1
	v_permlane32_swap_b32_e32 v18, v19
	v_add_f32_e32 v20, v18, v19
	v_cvt_f32_f16_sdwa v19, v70 dst_sel:DWORD dst_unused:UNUSED_PAD src0_sel:WORD_1
	v_cvt_f32_f16_e32 v18, v70
	v_add_f32_e32 v15, v15, v19
	v_cvt_f16_f32_e32 v19, v15
	v_add_f32_e32 v14, v14, v18
	v_cvt_f16_f32_e32 v18, v14
	v_cvt_pk_f16_f32 v14, v14, v15
	v_cvt_f32_f16_e32 v15, v19
	v_cvt_f32_f16_sdwa v19, v71 dst_sel:DWORD dst_unused:UNUSED_PAD src0_sel:WORD_1
	v_mul_f32_e32 v15, v15, v15
	v_fma_mix_f32 v21, v18, v18, v15 op_sel_hi:[1,1,0]
	v_cvt_f32_f16_e32 v18, v71
	v_pk_add_f32 v[16:17], v[16:17], v[18:19]
	s_nop 0
	v_cvt_pk_f16_f32 v15, v16, v17
	v_fma_mix_f32 v16, v15, v15, v21 op_sel_hi:[1,1,0]
	v_cvt_f32_f16_sdwa v17, v72 dst_sel:DWORD dst_unused:UNUSED_PAD src0_sel:WORD_1
	v_fma_mix_f32 v18, v15, v15, v16 op_sel:[1,1,0] op_sel_hi:[1,1,0]
	v_cvt_f32_f16_e32 v16, v72
	v_pk_add_f32 v[10:11], v[10:11], v[16:17]
	s_nop 0
	v_cvt_pk_f16_f32 v16, v10, v11
	v_fma_mix_f32 v10, v16, v16, v18 op_sel_hi:[1,1,0]
	v_cvt_f32_f16_sdwa v11, v73 dst_sel:DWORD dst_unused:UNUSED_PAD src0_sel:WORD_1
	v_fma_mix_f32 v18, v16, v16, v10 op_sel:[1,1,0] op_sel_hi:[1,1,0]
	v_cvt_f32_f16_e32 v10, v73
	v_pk_add_f32 v[10:11], v[12:13], v[10:11]
	v_cvt_f32_f16_e32 v13, v66
	v_cvt_pk_f16_f32 v17, v10, v11
	v_fma_mix_f32 v10, v17, v17, v18 op_sel_hi:[1,1,0]
	v_add_f32_e32 v6, v6, v13
	v_cvt_f16_f32_e32 v13, v6
	v_fma_mix_f32 v12, v17, v17, v10 op_sel:[1,1,0] op_sel_hi:[1,1,0]
	v_lshl_add_u64 v[10:11], s[40:41], 0, v[94:95]
	v_lshl_add_u64 v[10:11], v[10:11], 0, v[160:161]
	v_fma_mix_f32 v12, v13, v13, v12 op_sel_hi:[1,1,0]
	v_cvt_f32_f16_sdwa v13, v66 dst_sel:DWORD dst_unused:UNUSED_PAD src0_sel:WORD_1
	global_store_dwordx4 v[10:11], v[14:17], off
	v_add_f32_e32 v7, v7, v13
	v_cvt_f16_f32_e32 v13, v7
	v_cvt_pk_f16_f32 v6, v6, v7
	v_fma_mix_f32 v14, v13, v13, v12 op_sel_hi:[1,1,0]
	v_cvt_f32_f16_e32 v12, v67
	v_cvt_f32_f16_sdwa v13, v67 dst_sel:DWORD dst_unused:UNUSED_PAD src0_sel:WORD_1
	v_pk_add_f32 v[8:9], v[8:9], v[12:13]
	s_nop 0
	v_cvt_pk_f16_f32 v7, v8, v9
	v_fma_mix_f32 v8, v7, v7, v14 op_sel_hi:[1,1,0]
	v_cvt_f32_f16_sdwa v9, v68 dst_sel:DWORD dst_unused:UNUSED_PAD src0_sel:WORD_1
	v_fma_mix_f32 v12, v7, v7, v8 op_sel:[1,1,0] op_sel_hi:[1,1,0]
	v_cvt_f32_f16_e32 v8, v68
	v_pk_add_f32 v[2:3], v[2:3], v[8:9]
	s_nop 0
	v_cvt_pk_f16_f32 v8, v2, v3
	v_fma_mix_f32 v2, v8, v8, v12 op_sel_hi:[1,1,0]
	v_cvt_f32_f16_sdwa v3, v69 dst_sel:DWORD dst_unused:UNUSED_PAD src0_sel:WORD_1
	v_fma_mix_f32 v12, v8, v8, v2 op_sel:[1,1,0] op_sel_hi:[1,1,0]
	v_cvt_f32_f16_e32 v2, v69
	v_pk_add_f32 v[2:3], v[4:5], v[2:3]
	s_nop 0
	v_cvt_pk_f16_f32 v9, v2, v3
	v_fma_mix_f32 v2, v9, v9, v12 op_sel_hi:[1,1,0]
	global_store_dwordx4 v[10:11], v[6:9], off offset:64
	v_fma_mix_f32 v2, v9, v9, v2 op_sel:[1,1,0] op_sel_hi:[1,1,0]
	s_nop 0
	v_mov_b32_e32 v3, v2
	s_nop 1
	v_permlane16_swap_b32_e32 v2, v3
	v_add_f32_e32 v2, v2, v3
	v_mov_b32_e32 v3, v2
	s_nop 1
	v_permlane32_swap_b32_e32 v2, v3
	v_add_f32_e32 v2, v2, v3
	v_cndmask_b32_e32 v3, v34, v50, vcc
	v_cndmask_b32_e32 v2, v2, v20, vcc
	v_cndmask_b32_e64 v4, v2, v3, s[0:1]
	v_add_u32_e32 v2, 0x80, v158
	v_ashrrev_i32_e32 v3, 31, v2
	v_lshlrev_b64 v[2:3], 6, v[2:3]
	v_lshl_add_u64 v[2:3], s[10:11], 0, v[2:3]
	v_lshl_add_u64 v[2:3], v[2:3], 0, s[72:73]
	v_lshl_add_u64 v[2:3], v[2:3], 0, s[34:35]
	global_store_dword v[2:3], v4, off
	s_andn2_b64 vcc, exec, s[4:5]
	s_mov_b64 s[0:1], -1
	s_cbranch_vccnz .LBB0_479

; #define LAS __attribute__((address_space(3)))
; __global__ void __launch_bounds__(NTHREADS, 2) hymba_fwd(Args a) {
;     extern __shared__ __attribute__((aligned(16))) unsigned char lds_raw[];
;     LAS unsigned char* lds = (LAS unsigned char*)lds_raw;
;     if (threadIdx.x < 2) ((volatile LAS unsigned*)(lds + LDS_MISC))[threadIdx.x] = 0u;
;     __syncthreads();
	.amdhsa_kernel _Z9hymba_fwd4Args
		.amdhsa_group_segment_fixed_size 0
		.amdhsa_private_segment_fixed_size 0
		.amdhsa_kernarg_size 352
		.amdhsa_user_sgpr_count 2
		.amdhsa_user_sgpr_dispatch_ptr 0
		.amdhsa_user_sgpr_queue_ptr 0
		.amdhsa_user_sgpr_kernarg_segment_ptr 1
		.amdhsa_user_sgpr_dispatch_id 0
		.amdhsa_user_sgpr_kernarg_preload_length 0
		.amdhsa_user_sgpr_kernarg_preload_offset 0
		.amdhsa_user_sgpr_private_segment_size 0
		.amdhsa_uses_dynamic_stack 0
		.amdhsa_enable_private_segment 0
		.amdhsa_system_sgpr_workgroup_id_x 1
		.amdhsa_system_sgpr_workgroup_id_y 0
		.amdhsa_system_sgpr_workgroup_id_z 0
		.amdhsa_system_sgpr_workgroup_info 0
		.amdhsa_system_vgpr_workitem_id 0
		.amdhsa_next_free_vgpr 256
		.amdhsa_next_free_sgpr 102
		.amdhsa_accum_offset 256
		.amdhsa_reserve_vcc 1
		.amdhsa_float_round_mode_32 0
		.amdhsa_float_round_mode_16_64 0
		.amdhsa_float_denorm_mode_32 3
		.amdhsa_float_denorm_mode_16_64 3
		.amdhsa_dx10_clamp 1
		.amdhsa_ieee_mode 1
		.amdhsa_fp16_overflow 0
		.amdhsa_tg_split 0
		.amdhsa_exception_fp_ieee_invalid_op 0
		.amdhsa_exception_fp_denorm_src 0
		.amdhsa_exception_fp_ieee_div_zero 0
		.amdhsa_exception_fp_ieee_overflow 0
		.amdhsa_exception_fp_ieee_underflow 0
		.amdhsa_exception_fp_ieee_inexact 0
		.amdhsa_exception_int_div_zero 0
	.end_amdhsa_kernel

; #define LAS __attribute__((address_space(3)))
; __global__ void __launch_bounds__(NTHREADS, 2) hymba_fwd(Args a) {
;     extern __shared__ __attribute__((aligned(16))) unsigned char lds_raw[];
;     LAS unsigned char* lds = (LAS unsigned char*)lds_raw;
;     if (threadIdx.x < 2) ((volatile LAS unsigned*)(lds + LDS_MISC))[threadIdx.x] = 0u;
;     __syncthreads();
amdhsa.kernels:
  - .agpr_count:     0
    .args:
      - .offset:         0
        .size:           96
        .value_kind:     by_value
      - .offset:         96
        .size:           4
        .value_kind:     hidden_block_count_x
      - .offset:         100
        .size:           4
        .value_kind:     hidden_block_count_y
      - .offset:         104
        .size:           4
        .value_kind:     hidden_block_count_z
      - .offset:         108
        .size:           2
        .value_kind:     hidden_group_size_x
      - .offset:         110
        .size:           2
        .value_kind:     hidden_group_size_y
      - .offset:         112
        .size:           2
        .value_kind:     hidden_group_size_z
      - .offset:         114
        .size:           2
        .value_kind:     hidden_remainder_x
      - .offset:         116
        .size:           2
        .value_kind:     hidden_remainder_y
      - .offset:         118
        .size:           2
        .value_kind:     hidden_remainder_z
      - .offset:         136
        .size:           8
        .value_kind:     hidden_global_offset_x
      - .offset:         144
        .size:           8
        .value_kind:     hidden_global_offset_y
      - .offset:         152
        .size:           8
        .value_kind:     hidden_global_offset_z
      - .offset:         160
        .size:           2
        .value_kind:     hidden_grid_dims
      - .offset:         216
        .size:           4
        .value_kind:     hidden_dynamic_lds_size
    .group_segment_fixed_size: 0
    .kernarg_segment_align: 8
    .kernarg_segment_size: 352
    .language:       OpenCL C
    .language_version:
      - 2
      - 0
    .max_flat_workgroup_size: 512
    .name:           _Z9hymba_fwd4Args
    .private_segment_fixed_size: 0
    .sgpr_count:     108
    .sgpr_spill_count: 90
    .symbol:         _Z9hymba_fwd4Args.kd
    .uniform_work_group_size: 1
    .uses_dynamic_stack: false
    .vgpr_count:     256
    .vgpr_spill_count: 0
    .wavefront_size: 64
